# P1: second half of the SwiGLU epilogue (acc v0-v63) moved into the next unit's peeled first K-iteration, overlapping its LDS reads / barrier wait
# speedup vs baseline: 1.0123x; 1.0023x over previous
; #define PG8_STAGE(bufoff, gbase, voff) do { _Pragma("unroll") for (int _i = 0; _i < 2; ++_i) \
;         __builtin_amdgcn_global_load_lds((const unsigned*)((const char*)(gbase) + (voff)[_i]), (PG8_LAS unsigned*)(lds + (bufoff) + ldsw + _i * 8192), 16, 0, 0); } while (0)
; #define PG8_WAIT_V(n) asm volatile("s_waitcnt vmcnt(" #n ")" ::: "memory")
; #define PG8_BAR __builtin_amdgcn_s_barrier()
; template <class Epi, class Sched, bool ALIGN_EPI = false, bool SP2 = false>
; __device__ __forceinline__ void gemm_phase(PG8_LAS unsigned char* lds, const Gemm g, const Sched& S, const Epi& E) {
;     ...
;     for (int i = 0; i < 2; ++i) { int R, C; stage_rc(tid * 16 + i * 8192, R, C); const int Rb = Epi::PERM ? ((R & ~31) + perm32(R & 31)) : R;
;         voffA[i] = (unsigned)(R * K + C) * 2u; voffB[i] = (unsigned)(Rb * K + C) * 2u; }
;     const size_t kstep = (size_t)(BK * 2);
;     const size_t hstep = (size_t)HALF * K * 2;
;     const size_t tstep = 2 * hstep;
;     const unsigned ldsw = (unsigned)wid * 1024u;
;     const int aoff = lds_byte(wr * 64 + fr, fq * 8), boff = lds_byte(wc * 32 + fr, fq * 8);
;     ...
;     Unit cur, nxt; int ui = 0;
;     if (!S.next(0, cur)) return;
;     f32x4 acc[2][2][4][2];
; #pragma unroll
;     for (int a = 0; a < 2; ++a)
; #pragma unroll
;         for (int b = 0; b < 2; ++b)
; #pragma unroll
;             for (int m = 0; m < 4; ++m)
; #pragma unroll
;                 for (int n = 0; n < 2; ++n) acc[a][b][m][n] = (f32x4){0.f, 0.f, 0.f, 0.f};
;     bf16x8 At[4][2], B0[2][2], B1[2][2];
;     const char* cA = (const char*)g.A + (size_t)cur.pm * tstep; const char* cB = (const char*)g.Bt + (size_t)cur.pn * tstep;
;     S.a_ready(cur);
;     if constexpr (SP2) {
;         PG8_STAGE(PG8_SB(0, 0), cB, voffB); PG8_STAGE(PG8_SB(0, 1), cB + hstep, voffB); PG8_STAGE(PG8_SA(0, 0), cA, voffA); PG8_STAGE(PG8_SA(0, 1), cA + hstep, voffA);
;         if (wr == 1) PG8_BAR;
;         PG8_WAIT_V(2); PG8_BAR;
;         PG8_STAGE(PG8_SB(1, 0), cB + kstep, voffB); PG8_STAGE(PG8_SA(1, 0), cA + kstep, voffA); PG8_STAGE(PG8_SB(1, 1), cB + hstep + kstep, voffB);
;         PG8_WAIT_V(6); PG8_BAR;
.LBB0_186:
	s_lshl_b32 s4, s4, 5
	s_and_b32 s14, s4, 0x60
	s_mov_b64 s[4:5], 0x80
	s_add_i32 m0, s21, 0x18000
	v_lshl_add_u64 v[6:7], v[6:7], 0, s[4:5]
	s_lshl_b32 s7, s6, 13
	s_lshl_b32 s15, s14, 7
	s_waitcnt vmcnt(2)
	s_barrier
	global_load_lds_dwordx4 v[6:7], off
	v_lshl_add_u64 v[4:5], v[4:5], 0, s[4:5]
	s_add_i32 m0, s21, 0x1a000
	s_add_i32 s42, s21, 0x8000
	s_add_i32 s43, s21, 0xa000
	global_load_lds_dwordx4 v[4:5], off
	v_lshl_add_u64 v[0:1], v[0:1], 0, s[4:5]
	s_mov_b32 m0, s42
	s_add_u32 s8, s24, 0x40080
	global_load_lds_dwordx4 v[0:1], off
	v_lshl_add_u64 v[0:1], v[2:3], 0, s[4:5]
	s_mov_b32 m0, s43
	s_addc_u32 s9, s25, 0
	global_load_lds_dwordx4 v[0:1], off
	s_add_i32 m0, s21, 0x1c000
	v_lshl_add_u64 v[0:1], s[8:9], 0, v[132:133]
	global_load_lds_dwordx4 v[0:1], off
	v_lshl_add_u64 v[0:1], s[8:9], 0, v[128:129]
	s_add_i32 m0, s21, 0x1e000
	s_cmpk_lt_u32 s1, 0x100
	global_load_lds_dwordx4 v[0:1], off
	v_lshrrev_b32_e32 v1, 1, v9
	v_and_b32_e32 v1, 24, v1
	v_and_b32_e32 v0, 15, v9
	v_lshlrev_b32_e32 v2, 1, v1
	v_lshl_or_b32 v144, s6, 6, v0
	v_lshl_or_b32 v0, v0, 6, v2
	v_lshlrev_b32_e32 v2, 2, v9
	v_and_b32_e32 v2, 32, v2
	v_bitop3_b32 v3, v0, s7, v2 bitop3:0xde
	v_bitop3_b32 v145, v0, s15, v2 bitop3:0xde
	v_lshlrev_b32_e32 v0, 14, v13
	v_and_b32_e32 v0, 0xffff8000, v0
	v_or_b32_e32 v146, s14, v1
	v_lshl_add_u32 v0, v12, 11, v0
	v_and_b32_e32 v1, 1, v13
	v_lshl_or_b32 v0, v1, 6, v0
	v_lshl_add_u32 v136, v14, 1, v0
	v_lshlrev_b32_e32 v0, 14, v8
	v_and_b32_e32 v0, 0xffff8000, v0
	s_waitcnt vmcnt(0)
	v_lshl_add_u32 v0, v10, 11, v0
	v_and_b32_e32 v1, 1, v8
	s_sext_i32_i8 s49, s0
	s_cselect_b64 s[6:7], -1, 0
	v_readlane_b32 s0, v235, 6
	v_lshl_or_b32 v0, v1, 6, v0
	s_add_i32 s46, 0, 0x10000
	s_add_i32 s47, 0, 0x14000
	s_ashr_i32 s44, s0, 31
	s_mov_b32 s45, s0
	v_mov_b32_e32 v137, v133
	v_lshl_add_u32 v138, v11, 1, v0
	v_mov_b32_e32 v139, v133
	v_mov_b64_e32 v[140:141], 0xb00
	v_mov_b64_e32 v[142:143], 0xaff
	v_add_u32_e32 v147, s46, v145
	v_add_u32_e32 v148, s47, v145
	v_add_u32_e32 v149, 0, v3
	s_movk_i32 s48, 0x1600
	s_barrier
	v_readlane_b32 s1, v235, 7
	s_mov_b32 s98, 0
	s_branch .LBB0_189

; __device__ __forceinline__ unsigned pk2(float lo, float hi) { return pg8::cvt_pk_bf16(lo, hi); }
; __device__ __forceinline__ float silu_f(float x) { return x * sigmoid_f(x); }
;     __host__ __device__ bool next(int i, Unit& u) const {
;         const long L = (long)i * G + c; if (L >= nwg) return false;
;         int wgid = (int)L; { const int q = nwg / NXCD, r = nwg % NXCD, xcd = wgid % NXCD, off = wgid / NXCD; wgid = (xcd < r ? xcd * (q + 1) : r * (q + 1) + (xcd - r) * q) + off; }
;         const int nig = WGM * nN, gid = wgid / nig, fm = gid * WGM, gsz = (nM - fm) < WGM ? (nM - fm) : WGM;
;         u.pm = fm + ((wgid % nig) % gsz); u.pn = (wgid % nig) / gsz; return true;
;     }
;     __device__ __forceinline__ void operator()(const f32x4 (&acc)[2][2][4][2], const pg8::Unit& u, int wr, int wc, int fr, int fq) const {
;         const int row0 = u.pm * 256 + wr * 64 + fr, col = u.pn * 128 + wc * 32 + 8 * fq;
; #pragma unroll
;         for (int ai = 0; ai < 2; ++ai)
; #pragma unroll
;             for (int m = 0; m < 4; ++m) {
;                 const int row = row0 + ai * 128 + m * 16;
;                 const float rs = sumsq ? rsqrtf(sumsq[row] * (1.f / 1024.f) + EPS) : 1.f;
;                 float o[8];
; #pragma unroll
;                 for (int n = 0; n < 2; ++n)
; #pragma unroll
;                     for (int e = 0; e < 4; ++e) { const float g = acc[ai][0][m][n][e] * rs, up = acc[ai][1][m][n][e] * rs; o[4 * n + e] = silu_f(g) * up; }
;                 u32x4 w; w.x = pk2(o[0], o[1]); w.y = pk2(o[2], o[3]); w.z = pk2(o[4], o[5]); w.w = pk2(o[6], o[7]);
;                 *(u32x4*)(H + (size_t)row * DFF + col) = w;
.LBB0_189:
	s_add_i32 s41, s41, 1
	s_mul_i32 s0, s41, s44
	s_mul_hi_u32 s1, s41, s45
	s_add_i32 s1, s1, s0
	s_mul_i32 s0, s41, s45
	v_readlane_b32 s9, v235, 0
	s_add_u32 s16, s0, s9
	s_addc_u32 s17, s1, s36
	v_cmp_gt_i64_e32 vcc, s[16:17], v[142:143]
	v_cmp_lt_i64_e64 s[0:1], s[16:17], v[140:141]
	s_cbranch_vccnz .LBB0_191
	s_ashr_i32 s8, s16, 31
	s_lshr_b32 s8, s8, 29
	s_add_i32 s8, s16, s8
	s_ashr_i32 s9, s8, 3
	s_and_b32 s8, s8, -8
	s_sub_i32 s8, s16, s8
	s_cmp_lt_i32 s8, 0
	s_cselect_b32 s14, s37, 0x160
	s_mul_i32 s8, s8, s14
	s_add_i32 s8, s8, s9
	s_mul_hi_i32 s9, s8, 0x2e8ba2e9
	s_lshr_b32 s14, s9, 31
	s_ashr_i32 s9, s9, 4
	s_add_i32 s9, s9, s14
	s_lshl_b32 s14, s9, 2
	s_sub_i32 s15, 0x80, s14
	s_min_i32 s15, s15, 4
	s_abs_i32 s16, s15
	v_cvt_f32_u32_e32 v229, s16
	s_sub_i32 s18, 0, s16
	s_mulk_i32 s9, 0x58
	s_sub_i32 s9, s8, s9
	v_rcp_iflag_f32_e32 v229, v229
	s_abs_i32 s8, s9
	s_xor_b32 s17, s9, s15
	s_ashr_i32 s17, s17, 31
	v_mul_f32_e32 v229, 0x4f7ffffe, v229
	v_cvt_u32_f32_e32 v229, v229
	s_nop 0
	v_readfirstlane_b32 s19, v229
	s_mul_i32 s18, s18, s19
	s_mul_hi_u32 s18, s19, s18
	s_add_i32 s19, s19, s18
	s_mul_hi_u32 s18, s8, s19
	s_mul_i32 s19, s18, s16
	s_sub_i32 s8, s8, s19
	s_add_i32 s30, s18, 1
	s_sub_i32 s19, s8, s16
	s_cmp_ge_u32 s8, s16
	s_cselect_b32 s18, s30, s18
	s_cselect_b32 s8, s19, s8
	s_add_i32 s19, s18, 1
	s_cmp_ge_u32 s8, s16
	s_cselect_b32 s8, s19, s18
	s_xor_b32 s8, s8, s17
	s_sub_i32 s8, s8, s17
	s_mul_i32 s15, s8, s15
	s_sub_i32 s9, s9, s15
	s_add_i32 s14, s14, s9
.LBB0_191:
	s_ashr_i32 s15, s14, 31
	s_lshl_b64 s[16:17], s[14:15], 19
	v_readlane_b32 s18, v235, 31
	v_readlane_b32 s19, v235, 32
	s_add_u32 s16, s18, s16
	s_addc_u32 s17, s19, s17
	s_and_b64 s[18:19], s[0:1], exec
	s_cselect_b32 s15, s17, s23
	s_cselect_b32 s50, s16, s22
	s_ashr_i32 s9, s8, 31
	s_lshl_b64 s[18:19], s[8:9], 19
	s_add_u32 s18, s33, s18
	s_addc_u32 s19, s34, s19
	s_and_b64 s[30:31], s[0:1], exec
	s_cselect_b32 s9, s19, s25
	s_cselect_b32 s51, s18, s24
	s_add_u32 s22, s22, 0x40080
	s_addc_u32 s23, s23, 0
	s_add_u32 s52, s24, 0x100
	s_addc_u32 s53, s25, 0
	s_mov_b32 s54, -2
	s_cmp_eq_u32 s98, 0
	s_cbranch_scc1 .Lp1_plain
	ds_read_b128 v[150:153], v147
	ds_read_b128 v[154:157], v147 offset:1024
	ds_read_b128 v[158:161], v147 offset:2048
	ds_read_b128 v[162:165], v147 offset:3072
	ds_read_b128 v[166:169], v148
	ds_read_b128 v[170:173], v148 offset:1024
	ds_read_b128 v[174:177], v148 offset:2048
	ds_read_b128 v[178:181], v148 offset:3072
	s_add_u32 s24, s22, 0xfffc0080
	s_addc_u32 s25, s23, -1
	s_cmp_eq_u32 s54, 12
	s_cselect_b32 s31, s15, s25
	s_cselect_b32 s30, s50, s24
	s_cselect_b32 s25, s9, s53
	s_cselect_b32 s24, s51, s52
	v_lshl_add_u64 v[186:187], s[22:23], 0, v[136:137]
	s_add_i32 m0, s21, 0xc000
	ds_read_b128 v[182:185], v149
	ds_read_b128 v[192:195], v149 offset:1024
	ds_read_b128 v[196:199], v149 offset:2048
	ds_read_b128 v[200:203], v149 offset:3072
	ds_read_b128 v[204:207], v149 offset:4096
	ds_read_b128 v[208:211], v149 offset:5120
	ds_read_b128 v[212:215], v149 offset:6144
	ds_read_b128 v[216:219], v149 offset:7168
	global_load_lds_dwordx4 v[186:187], off
	v_lshl_add_u64 v[186:187], s[22:23], 0, v[138:139]
	s_add_i32 m0, s21, 0xe000
	s_nop 0
	global_load_lds_dwordx4 v[186:187], off
	s_nop 1
	v_add_f32_e32 v64, 1.0, v70
	v_rcp_f32_e32 v64, v64
	v_add_f32_e32 v65, 1.0, v71
	v_rcp_f32_e32 v65, v65
	v_add_u32_e32 v66, 0x80, v228
	v_mul_f32_e32 v60, v60, v64
	v_mul_f32_e32 v52, v60, v52
	v_mul_f32_e32 v60, v61, v65
	v_mul_f32_e32 v61, 0xbfb8aa3b, v62
	v_exp_f32_e32 v61, v61
	v_mul_f32_e32 v64, 0xbfb8aa3b, v63
	v_exp_f32_e32 v64, v64
	v_mul_f32_e32 v53, v60, v53
	v_add_f32_e32 v60, 1.0, v61
	v_rcp_f32_e32 v60, v60
	v_add_f32_e32 v61, 1.0, v64
	v_mul_f32_e32 v64, 0xbfb8aa3b, v56
	v_rcp_f32_e32 v61, v61
	v_exp_f32_e32 v64, v64
	v_mul_f32_e32 v60, v62, v60
	v_mul_f32_e32 v54, v60, v54
	v_mul_f32_e32 v60, v63, v61
	v_add_f32_e32 v61, 1.0, v64
	v_rcp_f32_e32 v61, v61
	v_mul_f32_e32 v62, 0xbfb8aa3b, v57
	v_exp_f32_e32 v62, v62
	v_mul_f32_e32 v55, v60, v55
	v_mul_f32_e32 v56, v56, v61
	v_mul_f32_e32 v56, v56, v48
	v_add_f32_e32 v48, 1.0, v62
	v_mul_f32_e32 v60, 0xbfb8aa3b, v58
	v_rcp_f32_e32 v48, v48
	v_exp_f32_e32 v60, v60
	v_mul_f32_e32 v61, 0xbfb8aa3b, v59
	v_exp_f32_e32 v61, v61
	v_mul_f32_e32 v48, v57, v48
	v_add_f32_e32 v57, 1.0, v60
	v_rcp_f32_e32 v57, v57
	v_add_f32_e32 v60, 1.0, v61
	v_rcp_f32_e32 v60, v60
	v_mul_f32_e32 v61, v48, v49
	v_mul_f32_e32 v48, v58, v57
	v_mul_f32_e32 v57, v48, v50
	v_mul_f32_e32 v48, v59, v60
	v_mul_f32_e32 v51, v48, v51
	v_cvt_pk_bf16_f32 v48, v52, v53
	v_cvt_pk_bf16_f32 v49, v54, v55
	v_mul_f32_e32 v54, 0xbfb8aa3b, v44
	v_exp_f32_e32 v54, v54
	v_mul_f32_e32 v55, 0xbfb8aa3b, v45
	v_exp_f32_e32 v55, v55
	v_mad_i64_i32 v[52:53], s[100:101], v66, s48, v[112:113]
	v_lshl_add_u64 v[52:53], v[52:53], 0, v[114:115]
	v_cvt_pk_bf16_f32 v50, v56, v61
	v_cvt_pk_bf16_f32 v51, v57, v51
	global_store_dwordx4 v[52:53], v[48:51], off
	s_nop 1
	v_add_f32_e32 v48, 1.0, v54
	v_rcp_f32_e32 v48, v48
	v_add_f32_e32 v49, 1.0, v55
	v_rcp_f32_e32 v49, v49
	v_add_u32_e32 v50, 0x90, v228
	v_mul_f32_e32 v44, v44, v48
	v_mul_f32_e32 v36, v44, v36
	v_mul_f32_e32 v44, v45, v49
	v_mul_f32_e32 v45, 0xbfb8aa3b, v46
	v_exp_f32_e32 v45, v45
	v_mul_f32_e32 v48, 0xbfb8aa3b, v47
	v_exp_f32_e32 v48, v48
	v_mul_f32_e32 v37, v44, v37
	v_add_f32_e32 v44, 1.0, v45
	v_rcp_f32_e32 v44, v44
	v_add_f32_e32 v45, 1.0, v48
	v_mul_f32_e32 v48, 0xbfb8aa3b, v40
	v_rcp_f32_e32 v45, v45
	v_exp_f32_e32 v48, v48
	v_mul_f32_e32 v44, v46, v44
	v_mul_f32_e32 v38, v44, v38
	v_mul_f32_e32 v44, v47, v45
	v_add_f32_e32 v45, 1.0, v48
	v_rcp_f32_e32 v45, v45
; #define PG8_STAGE(bufoff, gbase, voff) do { _Pragma("unroll") for (int _i = 0; _i < 2; ++_i) \
;         __builtin_amdgcn_global_load_lds((const unsigned*)((const char*)(gbase) + (voff)[_i]), (PG8_LAS unsigned*)(lds + (bufoff) + ldsw + _i * 8192), 16, 0, 0); } while (0)
; #define PG8_LDA(dst, b, h) do { _Pragma("unroll") for (int m = 0; m < 4; ++m) _Pragma("unroll") for (int k = 0; k < 2; ++k) dst[m][k] = *(const PG8_LAS bf16x8*)(lds + PG8_SA(b, h) + aoff + m * 2048 + k * 1024); } while (0)
; #define PG8_LDB(dst, b, h) do { _Pragma("unroll") for (int n = 0; n < 2; ++n) _Pragma("unroll") for (int k = 0; k < 2; ++k) dst[n][k] = *(const PG8_LAS bf16x8*)(lds + PG8_SB(b, h) + boff + n * 2048 + k * 1024); } while (0)
; #define PG8_WAIT_V(n) asm volatile("s_waitcnt vmcnt(" #n ")" ::: "memory")
; #define PG8_WAIT_L(n) asm volatile("s_waitcnt lgkmcnt(" #n ")" ::: "memory")
; #define PG8_BAR __builtin_amdgcn_s_barrier()
; #define PG8_SCHED __builtin_amdgcn_sched_barrier(0)
; template <class Epi, class Sched, bool ALIGN_EPI = false, bool SP2 = false>
; __device__ __forceinline__ void gemm_phase(PG8_LAS unsigned char* lds, const Gemm g, const Sched& S, const Epi& E) {
;     ...
;             PG8_LDB(B0, 0, 0); PG8_LDB(B1, 0, 1); PG8_SCHED; PG8_LDA(At, 0, 0); PG8_STAGE(PG8_SA(1, 1), a1 + hstep, voffA);
;             PG8_WAIT_V(8); PG8_WAIT_L(0); PG8_BAR; PG8_MMA(0, 0, At, B0); PG8_MMA(0, 1, At, B1); PG8_BAR; PG8_SCHED;
;     __device__ __forceinline__ void operator()(const f32x4 (&acc)[2][2][4][2], const pg8::Unit& u, int wr, int wc, int fr, int fq) const {
;         const int row0 = u.pm * 256 + wr * 64 + fr, col = u.pn * 128 + wc * 32 + 8 * fq;
; #pragma unroll
;         for (int ai = 0; ai < 2; ++ai)
; #pragma unroll
;             for (int m = 0; m < 4; ++m) {
;                 const int row = row0 + ai * 128 + m * 16;
;                 const float rs = sumsq ? rsqrtf(sumsq[row] * (1.f / 1024.f) + EPS) : 1.f;
;                 float o[8];
; #pragma unroll
;                 for (int n = 0; n < 2; ++n)
; #pragma unroll
;                     for (int e = 0; e < 4; ++e) { const float g = acc[ai][0][m][n][e] * rs, up = acc[ai][1][m][n][e] * rs; o[4 * n + e] = silu_f(g) * up; }
;                 u32x4 w; w.x = pk2(o[0], o[1]); w.y = pk2(o[2], o[3]); w.z = pk2(o[4], o[5]); w.w = pk2(o[6], o[7]);
;                 *(u32x4*)(H + (size_t)row * DFF + col) = w;
	v_mul_f32_e32 v46, 0xbfb8aa3b, v41
	v_exp_f32_e32 v46, v46
	v_mul_f32_e32 v39, v44, v39
	v_mul_f32_e32 v40, v40, v45
	v_mul_f32_e32 v40, v40, v32
	v_add_f32_e32 v32, 1.0, v46
	v_mul_f32_e32 v44, 0xbfb8aa3b, v42
	v_rcp_f32_e32 v32, v32
	v_exp_f32_e32 v44, v44
	v_mul_f32_e32 v45, 0xbfb8aa3b, v43
	v_exp_f32_e32 v45, v45
	v_mul_f32_e32 v32, v41, v32
	v_add_f32_e32 v41, 1.0, v44
	v_rcp_f32_e32 v41, v41
	v_add_f32_e32 v44, 1.0, v45
	v_rcp_f32_e32 v44, v44
	v_mul_f32_e32 v45, v32, v33
	v_mul_f32_e32 v32, v42, v41
	v_mul_f32_e32 v41, v32, v34
	v_mul_f32_e32 v32, v43, v44
	v_mul_f32_e32 v35, v32, v35
	v_cvt_pk_bf16_f32 v32, v36, v37
	v_cvt_pk_bf16_f32 v33, v38, v39
	v_mul_f32_e32 v38, 0xbfb8aa3b, v28
	v_exp_f32_e32 v38, v38
	v_mul_f32_e32 v39, 0xbfb8aa3b, v29
	v_exp_f32_e32 v39, v39
	v_mad_i64_i32 v[36:37], s[100:101], v50, s48, v[112:113]
	v_lshl_add_u64 v[36:37], v[36:37], 0, v[114:115]
	v_cvt_pk_bf16_f32 v34, v40, v45
	v_cvt_pk_bf16_f32 v35, v41, v35
	global_store_dwordx4 v[36:37], v[32:35], off
	s_nop 1
	v_add_f32_e32 v32, 1.0, v38
	v_rcp_f32_e32 v32, v32
	v_add_f32_e32 v33, 1.0, v39
	v_rcp_f32_e32 v33, v33
	v_add_u32_e32 v34, 0xa0, v228
	v_mul_f32_e32 v28, v28, v32
	v_mul_f32_e32 v20, v28, v20
	v_mul_f32_e32 v28, v29, v33
	v_mul_f32_e32 v29, 0xbfb8aa3b, v30
	v_exp_f32_e32 v29, v29
	v_mul_f32_e32 v32, 0xbfb8aa3b, v31
	v_exp_f32_e32 v32, v32
	v_mul_f32_e32 v21, v28, v21
	v_add_f32_e32 v28, 1.0, v29
	v_rcp_f32_e32 v28, v28
	v_add_f32_e32 v29, 1.0, v32
	v_mul_f32_e32 v32, 0xbfb8aa3b, v24
	v_rcp_f32_e32 v29, v29
	v_exp_f32_e32 v32, v32
	v_mul_f32_e32 v28, v30, v28
	v_mul_f32_e32 v22, v28, v22
	v_mul_f32_e32 v28, v31, v29
	v_add_f32_e32 v29, 1.0, v32
	v_rcp_f32_e32 v29, v29
	v_mul_f32_e32 v30, 0xbfb8aa3b, v25
	v_exp_f32_e32 v30, v30
	v_mul_f32_e32 v23, v28, v23
	v_mul_f32_e32 v24, v24, v29
	v_mul_f32_e32 v24, v24, v16
	v_add_f32_e32 v16, 1.0, v30
	v_mul_f32_e32 v28, 0xbfb8aa3b, v26
	v_rcp_f32_e32 v16, v16
	v_exp_f32_e32 v28, v28
	v_mul_f32_e32 v29, 0xbfb8aa3b, v27
	v_exp_f32_e32 v29, v29
	v_mul_f32_e32 v16, v25, v16
	v_add_f32_e32 v25, 1.0, v28
	v_rcp_f32_e32 v25, v25
	v_add_f32_e32 v28, 1.0, v29
	v_rcp_f32_e32 v28, v28
	v_mul_f32_e32 v29, v16, v17
	v_mul_f32_e32 v16, v26, v25
	v_mul_f32_e32 v25, v16, v18
	v_mul_f32_e32 v16, v27, v28
	v_mul_f32_e32 v19, v16, v19
	v_cvt_pk_bf16_f32 v16, v20, v21
	v_cvt_pk_bf16_f32 v17, v22, v23
	v_mul_f32_e32 v22, 0xbfb8aa3b, v12
	v_exp_f32_e32 v22, v22
	v_mul_f32_e32 v23, 0xbfb8aa3b, v13
	v_exp_f32_e32 v23, v23
	v_mad_i64_i32 v[20:21], s[100:101], v34, s48, v[112:113]
	v_lshl_add_u64 v[20:21], v[20:21], 0, v[114:115]
	v_cvt_pk_bf16_f32 v18, v24, v29
	v_cvt_pk_bf16_f32 v19, v25, v19
	global_store_dwordx4 v[20:21], v[16:19], off
	s_nop 1
	v_add_f32_e32 v16, 1.0, v22
	v_rcp_f32_e32 v16, v16
	v_add_f32_e32 v17, 1.0, v23
	v_rcp_f32_e32 v17, v17
	v_add_u32_e32 v18, 0xb0, v228
	v_mul_f32_e32 v12, v12, v16
	v_mul_f32_e32 v4, v12, v4
	v_mul_f32_e32 v12, v13, v17
	v_mul_f32_e32 v13, 0xbfb8aa3b, v14
	v_exp_f32_e32 v13, v13
	v_mul_f32_e32 v16, 0xbfb8aa3b, v15
	v_exp_f32_e32 v16, v16
	v_mul_f32_e32 v5, v12, v5
	v_add_f32_e32 v12, 1.0, v13
	v_rcp_f32_e32 v12, v12
	v_add_f32_e32 v13, 1.0, v16
	v_mul_f32_e32 v16, 0xbfb8aa3b, v8
	v_rcp_f32_e32 v13, v13
	v_exp_f32_e32 v16, v16
	v_mul_f32_e32 v12, v14, v12
	v_mul_f32_e32 v6, v12, v6
	v_mul_f32_e32 v12, v15, v13
	v_add_f32_e32 v13, 1.0, v16
	v_rcp_f32_e32 v13, v13
	v_mul_f32_e32 v14, 0xbfb8aa3b, v9
	v_exp_f32_e32 v14, v14
	v_mul_f32_e32 v7, v12, v7
	v_mul_f32_e32 v8, v8, v13
	v_mul_f32_e32 v8, v8, v0
	v_add_f32_e32 v0, 1.0, v14
	v_mul_f32_e32 v12, 0xbfb8aa3b, v10
	v_rcp_f32_e32 v0, v0
	v_exp_f32_e32 v12, v12
	v_mul_f32_e32 v13, 0xbfb8aa3b, v11
	v_exp_f32_e32 v13, v13
	v_mul_f32_e32 v0, v9, v0
	v_add_f32_e32 v9, 1.0, v12
	v_rcp_f32_e32 v9, v9
	v_add_f32_e32 v12, 1.0, v13
	v_rcp_f32_e32 v12, v12
	v_mul_f32_e32 v13, v0, v1
	v_mul_f32_e32 v0, v10, v9
	v_mul_f32_e32 v9, v0, v2
	v_mul_f32_e32 v0, v11, v12
	v_mul_f32_e32 v3, v0, v3
	v_cvt_pk_bf16_f32 v0, v4, v5
	v_mad_i64_i32 v[4:5], s[100:101], v18, s48, v[112:113]
	v_lshl_add_u64 v[4:5], v[4:5], 0, v[114:115]
	v_cvt_pk_bf16_f32 v1, v6, v7
	v_cvt_pk_bf16_f32 v2, v8, v13
	v_cvt_pk_bf16_f32 v3, v9, v3
	global_store_dwordx4 v[4:5], v[0:3], off
	s_waitcnt vmcnt(16)
	s_waitcnt lgkmcnt(0)
	s_barrier
	s_setprio 1
	v_mfma_f32_16x16x32_bf16 v[124:127], v[150:153], v[182:185], 0
	v_mfma_f32_16x16x32_bf16 v[120:123], v[158:161], v[182:185], 0
	v_mfma_f32_16x16x32_bf16 v[108:111], v[150:153], v[196:199], 0
	v_mfma_f32_16x16x32_bf16 v[104:107], v[158:161], v[196:199], 0
	v_mfma_f32_16x16x32_bf16 v[92:95], v[150:153], v[204:207], 0
	v_mfma_f32_16x16x32_bf16 v[88:91], v[158:161], v[204:207], 0
	v_mfma_f32_16x16x32_bf16 v[76:79], v[150:153], v[212:215], 0
	v_mfma_f32_16x16x32_bf16 v[72:75], v[158:161], v[212:215], 0
	v_mfma_f32_16x16x32_bf16 v[124:127], v[154:157], v[192:195], v[124:127]
	v_mfma_f32_16x16x32_bf16 v[120:123], v[162:165], v[192:195], v[120:123]
	v_mfma_f32_16x16x32_bf16 v[108:111], v[154:157], v[200:203], v[108:111]
	v_mfma_f32_16x16x32_bf16 v[104:107], v[162:165], v[200:203], v[104:107]
	v_mfma_f32_16x16x32_bf16 v[92:95], v[154:157], v[208:211], v[92:95]
	v_mfma_f32_16x16x32_bf16 v[88:91], v[162:165], v[208:211], v[88:91]
	v_mfma_f32_16x16x32_bf16 v[76:79], v[154:157], v[216:219], v[76:79]
	v_mfma_f32_16x16x32_bf16 v[72:75], v[162:165], v[216:219], v[72:75]
	v_mfma_f32_16x16x32_bf16 v[116:119], v[166:169], v[182:185], 0
	v_mfma_f32_16x16x32_bf16 v[112:115], v[174:177], v[182:185], 0
	v_mfma_f32_16x16x32_bf16 v[100:103], v[166:169], v[196:199], 0
	v_mfma_f32_16x16x32_bf16 v[96:99], v[174:177], v[196:199], 0
	v_mfma_f32_16x16x32_bf16 v[84:87], v[166:169], v[204:207], 0
	v_mfma_f32_16x16x32_bf16 v[80:83], v[174:177], v[204:207], 0
	v_mfma_f32_16x16x32_bf16 v[68:71], v[166:169], v[212:215], 0
	v_mfma_f32_16x16x32_bf16 v[64:67], v[174:177], v[212:215], 0
	v_mfma_f32_16x16x32_bf16 v[116:119], v[170:173], v[192:195], v[116:119]
	v_mfma_f32_16x16x32_bf16 v[112:115], v[178:181], v[192:195], v[112:115]
	v_mfma_f32_16x16x32_bf16 v[100:103], v[170:173], v[200:203], v[100:103]
	v_mfma_f32_16x16x32_bf16 v[96:99], v[178:181], v[200:203], v[96:99]
	v_mfma_f32_16x16x32_bf16 v[84:87], v[170:173], v[208:211], v[84:87]
	v_mfma_f32_16x16x32_bf16 v[80:83], v[178:181], v[208:211], v[80:83]
	v_mfma_f32_16x16x32_bf16 v[68:71], v[170:173], v[216:219], v[68:71]
	v_mfma_f32_16x16x32_bf16 v[64:67], v[178:181], v[216:219], v[64:67]
	s_setprio 0
	s_barrier
; #define PG8_STAGE(bufoff, gbase, voff) do { _Pragma("unroll") for (int _i = 0; _i < 2; ++_i) \
;         __builtin_amdgcn_global_load_lds((const unsigned*)((const char*)(gbase) + (voff)[_i]), (PG8_LAS unsigned*)(lds + (bufoff) + ldsw + _i * 8192), 16, 0, 0); } while (0)
; #define PG8_LDA(dst, b, h) do { _Pragma("unroll") for (int m = 0; m < 4; ++m) _Pragma("unroll") for (int k = 0; k < 2; ++k) dst[m][k] = *(const PG8_LAS bf16x8*)(lds + PG8_SA(b, h) + aoff + m * 2048 + k * 1024); } while (0)
; #define PG8_LDB(dst, b, h) do { _Pragma("unroll") for (int n = 0; n < 2; ++n) _Pragma("unroll") for (int k = 0; k < 2; ++k) dst[n][k] = *(const PG8_LAS bf16x8*)(lds + PG8_SB(b, h) + boff + n * 2048 + k * 1024); } while (0)
; #define PG8_MMA(ai, bj, At, Bt) do { __builtin_amdgcn_s_setprio(1); _Pragma("unroll") for (int m = 0; m < 4; ++m) _Pragma("unroll") for (int n = 0; n < 2; ++n) _Pragma("unroll") for (int k = 0; k < 2; ++k) \
;         acc[ai][bj][m][n] = __builtin_amdgcn_mfma_f32_16x16x32_bf16(Bt[n][k], At[m][k], acc[ai][bj][m][n], 0, 0, 0); __builtin_amdgcn_s_setprio(0); } while (0)
; #define PG8_WAIT_V(n) asm volatile("s_waitcnt vmcnt(" #n ")" ::: "memory")
; #define PG8_WAIT_L(n) asm volatile("s_waitcnt lgkmcnt(" #n ")" ::: "memory")
; #define PG8_BAR __builtin_amdgcn_s_barrier()
; #define PG8_SCHED __builtin_amdgcn_sched_barrier(0)
; template <class Epi, class Sched, bool ALIGN_EPI = false, bool SP2 = false>
; __device__ __forceinline__ void gemm_phase(PG8_LAS unsigned char* lds, const Gemm g, const Sched& S, const Epi& E) {
;     ...
;             PG8_LDA(At, 0, 1); PG8_STAGE(PG8_SB(0, 0), b2, voffB); PG8_STAGE(PG8_SB(0, 1), b2 + hstep, voffB); PG8_STAGE(PG8_SA(0, 0), a2, voffA);
;             PG8_WAIT_V(8); PG8_WAIT_L(0); PG8_BAR; PG8_MMA(1, 0, At, B0); PG8_MMA(1, 1, At, B1); PG8_BAR; PG8_SCHED;
;             PG8_LDB(B0, 1, 0); PG8_LDB(B1, 1, 1); PG8_SCHED; PG8_LDA(At, 1, 0); PG8_STAGE(PG8_SA(0, 1), a2 + hstep, voffA);
;             PG8_WAIT_V(8); PG8_WAIT_L(0); PG8_BAR; PG8_MMA(0, 0, At, B0); PG8_MMA(0, 1, At, B1); PG8_BAR; PG8_SCHED;
	s_add_i32 s55, s46, s35
	v_lshl_add_u64 v[186:187], s[24:25], 0, v[132:133]
	s_mov_b32 m0, s55
	ds_read_b128 v[182:185], v149 offset:16384
	ds_read_b128 v[192:195], v149 offset:17408
	ds_read_b128 v[196:199], v149 offset:18432
	ds_read_b128 v[200:203], v149 offset:19456
	ds_read_b128 v[204:207], v149 offset:20480
	ds_read_b128 v[208:211], v149 offset:21504
	ds_read_b128 v[212:215], v149 offset:22528
	ds_read_b128 v[216:219], v149 offset:23552
	global_load_lds_dwordx4 v[186:187], off
	s_add_i32 m0, s55, 0x2000
	s_add_u32 s56, s24, 0x40000
	v_lshl_add_u64 v[220:221], s[24:25], 0, v[128:129]
	s_addc_u32 s57, s25, 0
	s_add_i32 s55, s47, s35
	global_load_lds_dwordx4 v[220:221], off
	v_lshl_add_u64 v[222:223], s[56:57], 0, v[132:133]
	s_mov_b32 m0, s55
	v_lshl_add_u64 v[224:225], s[30:31], 0, v[130:131]
	global_load_lds_dwordx4 v[222:223], off
	v_lshl_add_u64 v[222:223], s[56:57], 0, v[128:129]
	s_add_i32 m0, s55, 0x2000
	s_nop 0
	global_load_lds_dwordx4 v[222:223], off
	v_lshl_add_u64 v[222:223], s[30:31], 0, v[134:135]
	s_mov_b32 m0, s21
	s_nop 0
	global_load_lds_dwordx4 v[222:223], off
	s_mov_b32 m0, s38
	s_nop 0
	global_load_lds_dwordx4 v[224:225], off
	s_waitcnt vmcnt(16)
	s_waitcnt lgkmcnt(0)
	s_barrier
	s_setprio 1
	v_mfma_f32_16x16x32_bf16 v[60:63], v[150:153], v[182:185], 0
	v_mfma_f32_16x16x32_bf16 v[56:59], v[158:161], v[182:185], 0
	v_mfma_f32_16x16x32_bf16 v[44:47], v[150:153], v[196:199], 0
	v_mfma_f32_16x16x32_bf16 v[40:43], v[158:161], v[196:199], 0
	v_mfma_f32_16x16x32_bf16 v[28:31], v[150:153], v[204:207], 0
	v_mfma_f32_16x16x32_bf16 v[24:27], v[158:161], v[204:207], 0
	v_mfma_f32_16x16x32_bf16 v[12:15], v[150:153], v[212:215], 0
	v_mfma_f32_16x16x32_bf16 v[8:11], v[158:161], v[212:215], 0
	v_mfma_f32_16x16x32_bf16 v[60:63], v[154:157], v[192:195], v[60:63]
	v_mfma_f32_16x16x32_bf16 v[56:59], v[162:165], v[192:195], v[56:59]
	v_mfma_f32_16x16x32_bf16 v[44:47], v[154:157], v[200:203], v[44:47]
	v_mfma_f32_16x16x32_bf16 v[40:43], v[162:165], v[200:203], v[40:43]
	v_mfma_f32_16x16x32_bf16 v[28:31], v[154:157], v[208:211], v[28:31]
	v_mfma_f32_16x16x32_bf16 v[24:27], v[162:165], v[208:211], v[24:27]
	v_mfma_f32_16x16x32_bf16 v[12:15], v[154:157], v[216:219], v[12:15]
	v_mfma_f32_16x16x32_bf16 v[8:11], v[162:165], v[216:219], v[8:11]
	v_mfma_f32_16x16x32_bf16 v[52:55], v[166:169], v[182:185], 0
	v_mfma_f32_16x16x32_bf16 v[48:51], v[174:177], v[182:185], 0
	v_mfma_f32_16x16x32_bf16 v[36:39], v[166:169], v[196:199], 0
	v_mfma_f32_16x16x32_bf16 v[32:35], v[174:177], v[196:199], 0
	v_mfma_f32_16x16x32_bf16 v[20:23], v[166:169], v[204:207], 0
	v_mfma_f32_16x16x32_bf16 v[16:19], v[174:177], v[204:207], 0
	v_mfma_f32_16x16x32_bf16 v[4:7], v[166:169], v[212:215], 0
	v_mfma_f32_16x16x32_bf16 v[0:3], v[174:177], v[212:215], 0
	v_mfma_f32_16x16x32_bf16 v[52:55], v[170:173], v[192:195], v[52:55]
	v_mfma_f32_16x16x32_bf16 v[48:51], v[178:181], v[192:195], v[48:51]
	v_mfma_f32_16x16x32_bf16 v[36:39], v[170:173], v[200:203], v[36:39]
	v_mfma_f32_16x16x32_bf16 v[32:35], v[178:181], v[200:203], v[32:35]
	v_mfma_f32_16x16x32_bf16 v[20:23], v[170:173], v[208:211], v[20:23]
	v_mfma_f32_16x16x32_bf16 v[16:19], v[178:181], v[208:211], v[16:19]
	v_mfma_f32_16x16x32_bf16 v[4:7], v[170:173], v[216:219], v[4:7]
	v_mfma_f32_16x16x32_bf16 v[0:3], v[178:181], v[216:219], v[0:3]
	s_setprio 0
	s_barrier
	s_add_i32 s55, 0, 0x18000
	s_add_i32 s56, 0, 0x1c000
	v_add_u32_e32 v162, s55, v145
	v_add_u32_e32 v178, s56, v145
	ds_read_b128 v[150:153], v162
	ds_read_b128 v[154:157], v162 offset:1024
	ds_read_b128 v[158:161], v162 offset:2048
	ds_read_b128 v[162:165], v162 offset:3072
	ds_read_b128 v[166:169], v178
	ds_read_b128 v[170:173], v178 offset:1024
	ds_read_b128 v[174:177], v178 offset:2048
	ds_read_b128 v[178:181], v178 offset:3072
	s_add_u32 s30, s30, 0x40000
	s_addc_u32 s31, s31, 0
	s_mov_b32 m0, s39
	v_lshl_add_u64 v[226:227], s[30:31], 0, v[134:135]
	ds_read_b128 v[182:185], v149 offset:32768
	ds_read_b128 v[192:195], v149 offset:33792
	ds_read_b128 v[196:199], v149 offset:34816
	ds_read_b128 v[200:203], v149 offset:35840
	ds_read_b128 v[204:207], v149 offset:36864
	ds_read_b128 v[208:211], v149 offset:37888
	ds_read_b128 v[212:215], v149 offset:38912
	ds_read_b128 v[216:219], v149 offset:39936
	global_load_lds_dwordx4 v[226:227], off
	v_lshl_add_u64 v[226:227], s[30:31], 0, v[130:131]
	s_mov_b32 m0, s40
	s_nop 0
	global_load_lds_dwordx4 v[226:227], off
	s_waitcnt vmcnt(8)
	s_waitcnt lgkmcnt(0)
	s_barrier
	s_setprio 1
	v_mfma_f32_16x16x32_bf16 v[124:127], v[150:153], v[182:185], v[124:127]
	v_mfma_f32_16x16x32_bf16 v[120:123], v[158:161], v[182:185], v[120:123]
	v_mfma_f32_16x16x32_bf16 v[108:111], v[150:153], v[196:199], v[108:111]
	v_mfma_f32_16x16x32_bf16 v[104:107], v[158:161], v[196:199], v[104:107]
	v_mfma_f32_16x16x32_bf16 v[92:95], v[150:153], v[204:207], v[92:95]
	v_mfma_f32_16x16x32_bf16 v[88:91], v[158:161], v[204:207], v[88:91]
	v_mfma_f32_16x16x32_bf16 v[76:79], v[150:153], v[212:215], v[76:79]
	v_mfma_f32_16x16x32_bf16 v[72:75], v[158:161], v[212:215], v[72:75]
	v_mfma_f32_16x16x32_bf16 v[124:127], v[154:157], v[192:195], v[124:127]
	v_mfma_f32_16x16x32_bf16 v[120:123], v[162:165], v[192:195], v[120:123]
	v_mfma_f32_16x16x32_bf16 v[108:111], v[154:157], v[200:203], v[108:111]
	v_mfma_f32_16x16x32_bf16 v[104:107], v[162:165], v[200:203], v[104:107]
	v_mfma_f32_16x16x32_bf16 v[92:95], v[154:157], v[208:211], v[92:95]
	v_mfma_f32_16x16x32_bf16 v[88:91], v[162:165], v[208:211], v[88:91]
	v_mfma_f32_16x16x32_bf16 v[76:79], v[154:157], v[216:219], v[76:79]
	v_mfma_f32_16x16x32_bf16 v[72:75], v[162:165], v[216:219], v[72:75]
	v_mfma_f32_16x16x32_bf16 v[116:119], v[166:169], v[182:185], v[116:119]
	v_mfma_f32_16x16x32_bf16 v[112:115], v[174:177], v[182:185], v[112:115]
	v_mfma_f32_16x16x32_bf16 v[100:103], v[166:169], v[196:199], v[100:103]
	v_mfma_f32_16x16x32_bf16 v[96:99], v[174:177], v[196:199], v[96:99]
	v_mfma_f32_16x16x32_bf16 v[84:87], v[166:169], v[204:207], v[84:87]
	v_mfma_f32_16x16x32_bf16 v[80:83], v[174:177], v[204:207], v[80:83]
	v_mfma_f32_16x16x32_bf16 v[68:71], v[166:169], v[212:215], v[68:71]
	v_mfma_f32_16x16x32_bf16 v[64:67], v[174:177], v[212:215], v[64:67]
	v_mfma_f32_16x16x32_bf16 v[116:119], v[170:173], v[192:195], v[116:119]
	v_mfma_f32_16x16x32_bf16 v[112:115], v[178:181], v[192:195], v[112:115]
	v_mfma_f32_16x16x32_bf16 v[100:103], v[170:173], v[200:203], v[100:103]
	v_mfma_f32_16x16x32_bf16 v[96:99], v[178:181], v[200:203], v[96:99]
	v_mfma_f32_16x16x32_bf16 v[84:87], v[170:173], v[208:211], v[84:87]
	v_mfma_f32_16x16x32_bf16 v[80:83], v[178:181], v[208:211], v[80:83]
	v_mfma_f32_16x16x32_bf16 v[68:71], v[170:173], v[216:219], v[68:71]
	v_mfma_f32_16x16x32_bf16 v[64:67], v[178:181], v[216:219], v[64:67]
	s_setprio 0
	s_barrier
; #define PG8_STAGE(bufoff, gbase, voff) do { _Pragma("unroll") for (int _i = 0; _i < 2; ++_i) \
;         __builtin_amdgcn_global_load_lds((const unsigned*)((const char*)(gbase) + (voff)[_i]), (PG8_LAS unsigned*)(lds + (bufoff) + ldsw + _i * 8192), 16, 0, 0); } while (0)
; #define PG8_LDA(dst, b, h) do { _Pragma("unroll") for (int m = 0; m < 4; ++m) _Pragma("unroll") for (int k = 0; k < 2; ++k) dst[m][k] = *(const PG8_LAS bf16x8*)(lds + PG8_SA(b, h) + aoff + m * 2048 + k * 1024); } while (0)
; #define PG8_LDB(dst, b, h) do { _Pragma("unroll") for (int n = 0; n < 2; ++n) _Pragma("unroll") for (int k = 0; k < 2; ++k) dst[n][k] = *(const PG8_LAS bf16x8*)(lds + PG8_SB(b, h) + boff + n * 2048 + k * 1024); } while (0)
; #define PG8_MMA(ai, bj, At, Bt) do { __builtin_amdgcn_s_setprio(1); _Pragma("unroll") for (int m = 0; m < 4; ++m) _Pragma("unroll") for (int n = 0; n < 2; ++n) _Pragma("unroll") for (int k = 0; k < 2; ++k) \
;         acc[ai][bj][m][n] = __builtin_amdgcn_mfma_f32_16x16x32_bf16(Bt[n][k], At[m][k], acc[ai][bj][m][n], 0, 0, 0); __builtin_amdgcn_s_setprio(0); } while (0)
; #define PG8_WAIT_V(n) asm volatile("s_waitcnt vmcnt(" #n ")" ::: "memory")
; template <class Epi, class Sched, bool ALIGN_EPI = false, bool SP2 = false>
; __device__ __forceinline__ void gemm_phase(PG8_LAS unsigned char* lds, const Gemm g, const Sched& S, const Epi& E) {
;     ...
;             PG8_LDB(B0, 0, 0); PG8_LDB(B1, 0, 1); PG8_SCHED; PG8_LDA(At, 0, 0); PG8_STAGE(PG8_SA(1, 1), a1 + hstep, voffA);
;             PG8_WAIT_V(8); PG8_WAIT_L(0); PG8_BAR; PG8_MMA(0, 0, At, B0); PG8_MMA(0, 1, At, B1); PG8_BAR; PG8_SCHED;
;             PG8_LDA(At, 0, 1); PG8_STAGE(PG8_SB(0, 0), b2, voffB); PG8_STAGE(PG8_SB(0, 1), b2 + hstep, voffB); PG8_STAGE(PG8_SA(0, 0), a2, voffA);
;             PG8_WAIT_V(8); PG8_WAIT_L(0); PG8_BAR; PG8_MMA(1, 0, At, B0); PG8_MMA(1, 1, At, B1); PG8_BAR; PG8_SCHED;
;             PG8_LDB(B0, 1, 0); PG8_LDB(B1, 1, 1); PG8_SCHED; PG8_LDA(At, 1, 0); PG8_STAGE(PG8_SA(0, 1), a2 + hstep, voffA);
;             PG8_WAIT_V(8); PG8_WAIT_L(0); PG8_BAR; PG8_MMA(0, 0, At, B0); PG8_MMA(0, 1, At, B1); PG8_BAR; PG8_SCHED;
;             PG8_LDA(At, 1, 1); PG8_STAGE(PG8_SB(1, 0), b3, voffB); PG8_STAGE(PG8_SB(1, 1), b3 + hstep, voffB); PG8_STAGE(PG8_SA(1, 0), a3, voffA);
;             PG8_WAIT_V(8); PG8_WAIT_L(0); PG8_BAR; PG8_MMA(1, 0, At, B0); PG8_MMA(1, 1, At, B1); PG8_BAR; PG8_SCHED;
	s_add_i32 s30, s55, s35
	v_lshl_add_u64 v[186:187], v[186:187], 0, s[4:5]
	s_mov_b32 m0, s30
	ds_read_b128 v[182:185], v149 offset:49152
	ds_read_b128 v[192:195], v149 offset:50176
	ds_read_b128 v[196:199], v149 offset:51200
	ds_read_b128 v[200:203], v149 offset:52224
	ds_read_b128 v[204:207], v149 offset:53248
	ds_read_b128 v[208:211], v149 offset:54272
	ds_read_b128 v[212:215], v149 offset:55296
	ds_read_b128 v[216:219], v149 offset:56320
	global_load_lds_dwordx4 v[186:187], off
	s_add_i32 m0, s30, 0x2000
	s_add_u32 s24, s24, 0x40080
	v_lshl_add_u64 v[186:187], v[220:221], 0, s[4:5]
	s_addc_u32 s25, s25, 0
	s_add_i32 s30, s56, s35
	global_load_lds_dwordx4 v[186:187], off
	v_lshl_add_u64 v[186:187], s[24:25], 0, v[132:133]
	s_mov_b32 m0, s30
	s_nop 0
	global_load_lds_dwordx4 v[186:187], off
	v_lshl_add_u64 v[186:187], s[24:25], 0, v[128:129]
	s_add_i32 m0, s30, 0x2000
	s_nop 0
	global_load_lds_dwordx4 v[186:187], off
	v_lshl_add_u64 v[186:187], v[222:223], 0, s[4:5]
	s_mov_b32 m0, s42
	s_nop 0
	global_load_lds_dwordx4 v[186:187], off
	v_lshl_add_u64 v[186:187], v[224:225], 0, s[4:5]
	s_mov_b32 m0, s43
	s_nop 0
	global_load_lds_dwordx4 v[186:187], off
	s_waitcnt vmcnt(8)
	s_waitcnt lgkmcnt(0)
	s_barrier
	s_setprio 1
	v_mfma_f32_16x16x32_bf16 v[60:63], v[150:153], v[182:185], v[60:63]
	v_mfma_f32_16x16x32_bf16 v[56:59], v[158:161], v[182:185], v[56:59]
	v_mfma_f32_16x16x32_bf16 v[44:47], v[150:153], v[196:199], v[44:47]
	v_mfma_f32_16x16x32_bf16 v[40:43], v[158:161], v[196:199], v[40:43]
	v_mfma_f32_16x16x32_bf16 v[28:31], v[150:153], v[204:207], v[28:31]
	v_mfma_f32_16x16x32_bf16 v[24:27], v[158:161], v[204:207], v[24:27]
	v_mfma_f32_16x16x32_bf16 v[12:15], v[150:153], v[212:215], v[12:15]
	v_mfma_f32_16x16x32_bf16 v[8:11], v[158:161], v[212:215], v[8:11]
	v_mfma_f32_16x16x32_bf16 v[60:63], v[154:157], v[192:195], v[60:63]
	v_mfma_f32_16x16x32_bf16 v[56:59], v[162:165], v[192:195], v[56:59]
	v_mfma_f32_16x16x32_bf16 v[44:47], v[154:157], v[200:203], v[44:47]
	v_mfma_f32_16x16x32_bf16 v[40:43], v[162:165], v[200:203], v[40:43]
	v_mfma_f32_16x16x32_bf16 v[28:31], v[154:157], v[208:211], v[28:31]
	v_mfma_f32_16x16x32_bf16 v[24:27], v[162:165], v[208:211], v[24:27]
	v_mfma_f32_16x16x32_bf16 v[12:15], v[154:157], v[216:219], v[12:15]
	v_mfma_f32_16x16x32_bf16 v[8:11], v[162:165], v[216:219], v[8:11]
	v_mfma_f32_16x16x32_bf16 v[52:55], v[166:169], v[182:185], v[52:55]
	v_mfma_f32_16x16x32_bf16 v[48:51], v[174:177], v[182:185], v[48:51]
	v_mfma_f32_16x16x32_bf16 v[36:39], v[166:169], v[196:199], v[36:39]
	v_mfma_f32_16x16x32_bf16 v[32:35], v[174:177], v[196:199], v[32:35]
	v_mfma_f32_16x16x32_bf16 v[20:23], v[166:169], v[204:207], v[20:23]
	v_mfma_f32_16x16x32_bf16 v[16:19], v[174:177], v[204:207], v[16:19]
	v_mfma_f32_16x16x32_bf16 v[4:7], v[166:169], v[212:215], v[4:7]
	v_mfma_f32_16x16x32_bf16 v[0:3], v[174:177], v[212:215], v[0:3]
	v_mfma_f32_16x16x32_bf16 v[52:55], v[170:173], v[192:195], v[52:55]
	v_mfma_f32_16x16x32_bf16 v[48:51], v[178:181], v[192:195], v[48:51]
	v_mfma_f32_16x16x32_bf16 v[36:39], v[170:173], v[200:203], v[36:39]
	v_mfma_f32_16x16x32_bf16 v[32:35], v[178:181], v[200:203], v[32:35]
	v_mfma_f32_16x16x32_bf16 v[20:23], v[170:173], v[208:211], v[20:23]
	v_mfma_f32_16x16x32_bf16 v[16:19], v[178:181], v[208:211], v[16:19]
	v_mfma_f32_16x16x32_bf16 v[4:7], v[170:173], v[216:219], v[4:7]
	v_mfma_f32_16x16x32_bf16 v[0:3], v[178:181], v[216:219], v[0:3]
	s_setprio 0
	s_barrier
	s_add_i32 s54, s54, 2
	s_add_u32 s22, s22, 0x100
	s_addc_u32 s23, s23, 0
	s_add_u32 s52, s52, 0x100
	s_addc_u32 s53, s53, 0
	s_branch .LBB0_192
.Lp1_plain:
	ds_read_b128 v[150:153], v147
	ds_read_b128 v[154:157], v147 offset:1024
	ds_read_b128 v[158:161], v147 offset:2048
	ds_read_b128 v[162:165], v147 offset:3072
	ds_read_b128 v[166:169], v148
	ds_read_b128 v[170:173], v148 offset:1024
	ds_read_b128 v[174:177], v148 offset:2048
	ds_read_b128 v[178:181], v148 offset:3072
	s_add_u32 s24, s22, 0xfffc0080
	s_addc_u32 s25, s23, -1
	s_cmp_eq_u32 s54, 12
	s_cselect_b32 s31, s15, s25
	s_cselect_b32 s30, s50, s24
	s_cselect_b32 s25, s9, s53
	s_cselect_b32 s24, s51, s52
	v_lshl_add_u64 v[186:187], s[22:23], 0, v[136:137]
	s_add_i32 m0, s21, 0xc000
	ds_read_b128 v[182:185], v149
	ds_read_b128 v[192:195], v149 offset:1024
	ds_read_b128 v[196:199], v149 offset:2048
	ds_read_b128 v[200:203], v149 offset:3072
	ds_read_b128 v[204:207], v149 offset:4096
	ds_read_b128 v[208:211], v149 offset:5120
	ds_read_b128 v[212:215], v149 offset:6144
	ds_read_b128 v[216:219], v149 offset:7168
	global_load_lds_dwordx4 v[186:187], off
	v_lshl_add_u64 v[186:187], s[22:23], 0, v[138:139]
	s_add_i32 m0, s21, 0xe000
	s_nop 0
	global_load_lds_dwordx4 v[186:187], off
	s_waitcnt vmcnt(16)
	s_waitcnt lgkmcnt(0)
	s_barrier
; #define PG8_STAGE(bufoff, gbase, voff) do { _Pragma("unroll") for (int _i = 0; _i < 2; ++_i) \
;         __builtin_amdgcn_global_load_lds((const unsigned*)((const char*)(gbase) + (voff)[_i]), (PG8_LAS unsigned*)(lds + (bufoff) + ldsw + _i * 8192), 16, 0, 0); } while (0)
; #define PG8_LDA(dst, b, h) do { _Pragma("unroll") for (int m = 0; m < 4; ++m) _Pragma("unroll") for (int k = 0; k < 2; ++k) dst[m][k] = *(const PG8_LAS bf16x8*)(lds + PG8_SA(b, h) + aoff + m * 2048 + k * 1024); } while (0)
; #define PG8_LDB(dst, b, h) do { _Pragma("unroll") for (int n = 0; n < 2; ++n) _Pragma("unroll") for (int k = 0; k < 2; ++k) dst[n][k] = *(const PG8_LAS bf16x8*)(lds + PG8_SB(b, h) + boff + n * 2048 + k * 1024); } while (0)
; #define PG8_MMA(ai, bj, At, Bt) do { __builtin_amdgcn_s_setprio(1); _Pragma("unroll") for (int m = 0; m < 4; ++m) _Pragma("unroll") for (int n = 0; n < 2; ++n) _Pragma("unroll") for (int k = 0; k < 2; ++k) \
;         acc[ai][bj][m][n] = __builtin_amdgcn_mfma_f32_16x16x32_bf16(Bt[n][k], At[m][k], acc[ai][bj][m][n], 0, 0, 0); __builtin_amdgcn_s_setprio(0); } while (0)
; #define PG8_WAIT_V(n) asm volatile("s_waitcnt vmcnt(" #n ")" ::: "memory")
; #define PG8_WAIT_L(n) asm volatile("s_waitcnt lgkmcnt(" #n ")" ::: "memory")
; #define PG8_BAR __builtin_amdgcn_s_barrier()
; #define PG8_SCHED __builtin_amdgcn_sched_barrier(0)
; template <class Epi, class Sched, bool ALIGN_EPI = false, bool SP2 = false>
; __device__ __forceinline__ void gemm_phase(PG8_LAS unsigned char* lds, const Gemm g, const Sched& S, const Epi& E) {
;     ...
;             PG8_LDB(B0, 0, 0); PG8_LDB(B1, 0, 1); PG8_SCHED; PG8_LDA(At, 0, 0); PG8_STAGE(PG8_SA(1, 1), a1 + hstep, voffA);
;             PG8_WAIT_V(8); PG8_WAIT_L(0); PG8_BAR; PG8_MMA(0, 0, At, B0); PG8_MMA(0, 1, At, B1); PG8_BAR; PG8_SCHED;
;             PG8_LDA(At, 0, 1); PG8_STAGE(PG8_SB(0, 0), b2, voffB); PG8_STAGE(PG8_SB(0, 1), b2 + hstep, voffB); PG8_STAGE(PG8_SA(0, 0), a2, voffA);
;             PG8_WAIT_V(8); PG8_WAIT_L(0); PG8_BAR; PG8_MMA(1, 0, At, B0); PG8_MMA(1, 1, At, B1); PG8_BAR; PG8_SCHED;
	s_setprio 1
	v_mfma_f32_16x16x32_bf16 v[124:127], v[150:153], v[182:185], 0
	v_mfma_f32_16x16x32_bf16 v[120:123], v[158:161], v[182:185], 0
	v_mfma_f32_16x16x32_bf16 v[108:111], v[150:153], v[196:199], 0
	v_mfma_f32_16x16x32_bf16 v[104:107], v[158:161], v[196:199], 0
	v_mfma_f32_16x16x32_bf16 v[92:95], v[150:153], v[204:207], 0
	v_mfma_f32_16x16x32_bf16 v[88:91], v[158:161], v[204:207], 0
	v_mfma_f32_16x16x32_bf16 v[76:79], v[150:153], v[212:215], 0
	v_mfma_f32_16x16x32_bf16 v[72:75], v[158:161], v[212:215], 0
	v_mfma_f32_16x16x32_bf16 v[124:127], v[154:157], v[192:195], v[124:127]
	v_mfma_f32_16x16x32_bf16 v[120:123], v[162:165], v[192:195], v[120:123]
	v_mfma_f32_16x16x32_bf16 v[108:111], v[154:157], v[200:203], v[108:111]
	v_mfma_f32_16x16x32_bf16 v[104:107], v[162:165], v[200:203], v[104:107]
	v_mfma_f32_16x16x32_bf16 v[92:95], v[154:157], v[208:211], v[92:95]
	v_mfma_f32_16x16x32_bf16 v[88:91], v[162:165], v[208:211], v[88:91]
	v_mfma_f32_16x16x32_bf16 v[76:79], v[154:157], v[216:219], v[76:79]
	v_mfma_f32_16x16x32_bf16 v[72:75], v[162:165], v[216:219], v[72:75]
	v_mfma_f32_16x16x32_bf16 v[116:119], v[166:169], v[182:185], 0
	v_mfma_f32_16x16x32_bf16 v[112:115], v[174:177], v[182:185], 0
	v_mfma_f32_16x16x32_bf16 v[100:103], v[166:169], v[196:199], 0
	v_mfma_f32_16x16x32_bf16 v[96:99], v[174:177], v[196:199], 0
	v_mfma_f32_16x16x32_bf16 v[84:87], v[166:169], v[204:207], 0
	v_mfma_f32_16x16x32_bf16 v[80:83], v[174:177], v[204:207], 0
	v_mfma_f32_16x16x32_bf16 v[68:71], v[166:169], v[212:215], 0
	v_mfma_f32_16x16x32_bf16 v[64:67], v[174:177], v[212:215], 0
	v_mfma_f32_16x16x32_bf16 v[116:119], v[170:173], v[192:195], v[116:119]
	v_mfma_f32_16x16x32_bf16 v[112:115], v[178:181], v[192:195], v[112:115]
	v_mfma_f32_16x16x32_bf16 v[100:103], v[170:173], v[200:203], v[100:103]
	v_mfma_f32_16x16x32_bf16 v[96:99], v[178:181], v[200:203], v[96:99]
	v_mfma_f32_16x16x32_bf16 v[84:87], v[170:173], v[208:211], v[84:87]
	v_mfma_f32_16x16x32_bf16 v[80:83], v[178:181], v[208:211], v[80:83]
	v_mfma_f32_16x16x32_bf16 v[68:71], v[170:173], v[216:219], v[68:71]
	v_mfma_f32_16x16x32_bf16 v[64:67], v[178:181], v[216:219], v[64:67]
	s_setprio 0
	s_barrier
	s_add_i32 s55, s46, s35
	v_lshl_add_u64 v[186:187], s[24:25], 0, v[132:133]
	s_mov_b32 m0, s55
	ds_read_b128 v[182:185], v149 offset:16384
	ds_read_b128 v[192:195], v149 offset:17408
	ds_read_b128 v[196:199], v149 offset:18432
	ds_read_b128 v[200:203], v149 offset:19456
	ds_read_b128 v[204:207], v149 offset:20480
	ds_read_b128 v[208:211], v149 offset:21504
	ds_read_b128 v[212:215], v149 offset:22528
	ds_read_b128 v[216:219], v149 offset:23552
	global_load_lds_dwordx4 v[186:187], off
	s_add_i32 m0, s55, 0x2000
	s_add_u32 s56, s24, 0x40000
	v_lshl_add_u64 v[220:221], s[24:25], 0, v[128:129]
	s_addc_u32 s57, s25, 0
	s_add_i32 s55, s47, s35
	global_load_lds_dwordx4 v[220:221], off
	v_lshl_add_u64 v[222:223], s[56:57], 0, v[132:133]
	s_mov_b32 m0, s55
	v_lshl_add_u64 v[224:225], s[30:31], 0, v[130:131]
	global_load_lds_dwordx4 v[222:223], off
	v_lshl_add_u64 v[222:223], s[56:57], 0, v[128:129]
	s_add_i32 m0, s55, 0x2000
	s_nop 0
	global_load_lds_dwordx4 v[222:223], off
	v_lshl_add_u64 v[222:223], s[30:31], 0, v[134:135]
	s_mov_b32 m0, s21
	s_nop 0
	global_load_lds_dwordx4 v[222:223], off
	s_mov_b32 m0, s38
	s_nop 0
	global_load_lds_dwordx4 v[224:225], off
	s_waitcnt vmcnt(16)
	s_waitcnt lgkmcnt(0)
	s_barrier
	s_setprio 1
	v_mfma_f32_16x16x32_bf16 v[60:63], v[150:153], v[182:185], 0
	v_mfma_f32_16x16x32_bf16 v[56:59], v[158:161], v[182:185], 0
	v_mfma_f32_16x16x32_bf16 v[44:47], v[150:153], v[196:199], 0
	v_mfma_f32_16x16x32_bf16 v[40:43], v[158:161], v[196:199], 0
	v_mfma_f32_16x16x32_bf16 v[28:31], v[150:153], v[204:207], 0
	v_mfma_f32_16x16x32_bf16 v[24:27], v[158:161], v[204:207], 0
	v_mfma_f32_16x16x32_bf16 v[12:15], v[150:153], v[212:215], 0
	v_mfma_f32_16x16x32_bf16 v[8:11], v[158:161], v[212:215], 0
	v_mfma_f32_16x16x32_bf16 v[60:63], v[154:157], v[192:195], v[60:63]
	v_mfma_f32_16x16x32_bf16 v[56:59], v[162:165], v[192:195], v[56:59]
	v_mfma_f32_16x16x32_bf16 v[44:47], v[154:157], v[200:203], v[44:47]
	v_mfma_f32_16x16x32_bf16 v[40:43], v[162:165], v[200:203], v[40:43]
	v_mfma_f32_16x16x32_bf16 v[28:31], v[154:157], v[208:211], v[28:31]
	v_mfma_f32_16x16x32_bf16 v[24:27], v[162:165], v[208:211], v[24:27]
	v_mfma_f32_16x16x32_bf16 v[12:15], v[154:157], v[216:219], v[12:15]
	v_mfma_f32_16x16x32_bf16 v[8:11], v[162:165], v[216:219], v[8:11]
	v_mfma_f32_16x16x32_bf16 v[52:55], v[166:169], v[182:185], 0
	v_mfma_f32_16x16x32_bf16 v[48:51], v[174:177], v[182:185], 0
	v_mfma_f32_16x16x32_bf16 v[36:39], v[166:169], v[196:199], 0
	v_mfma_f32_16x16x32_bf16 v[32:35], v[174:177], v[196:199], 0
	v_mfma_f32_16x16x32_bf16 v[20:23], v[166:169], v[204:207], 0
	v_mfma_f32_16x16x32_bf16 v[16:19], v[174:177], v[204:207], 0
	v_mfma_f32_16x16x32_bf16 v[4:7], v[166:169], v[212:215], 0
	v_mfma_f32_16x16x32_bf16 v[0:3], v[174:177], v[212:215], 0
	v_mfma_f32_16x16x32_bf16 v[52:55], v[170:173], v[192:195], v[52:55]
	v_mfma_f32_16x16x32_bf16 v[48:51], v[178:181], v[192:195], v[48:51]
	v_mfma_f32_16x16x32_bf16 v[36:39], v[170:173], v[200:203], v[36:39]
	v_mfma_f32_16x16x32_bf16 v[32:35], v[178:181], v[200:203], v[32:35]
	v_mfma_f32_16x16x32_bf16 v[20:23], v[170:173], v[208:211], v[20:23]
	v_mfma_f32_16x16x32_bf16 v[16:19], v[178:181], v[208:211], v[16:19]
	v_mfma_f32_16x16x32_bf16 v[4:7], v[170:173], v[216:219], v[4:7]
	v_mfma_f32_16x16x32_bf16 v[0:3], v[178:181], v[216:219], v[0:3]
	s_setprio 0
	s_barrier
; #define PG8_STAGE(bufoff, gbase, voff) do { _Pragma("unroll") for (int _i = 0; _i < 2; ++_i) \
;         __builtin_amdgcn_global_load_lds((const unsigned*)((const char*)(gbase) + (voff)[_i]), (PG8_LAS unsigned*)(lds + (bufoff) + ldsw + _i * 8192), 16, 0, 0); } while (0)
; #define PG8_LDA(dst, b, h) do { _Pragma("unroll") for (int m = 0; m < 4; ++m) _Pragma("unroll") for (int k = 0; k < 2; ++k) dst[m][k] = *(const PG8_LAS bf16x8*)(lds + PG8_SA(b, h) + aoff + m * 2048 + k * 1024); } while (0)
; #define PG8_LDB(dst, b, h) do { _Pragma("unroll") for (int n = 0; n < 2; ++n) _Pragma("unroll") for (int k = 0; k < 2; ++k) dst[n][k] = *(const PG8_LAS bf16x8*)(lds + PG8_SB(b, h) + boff + n * 2048 + k * 1024); } while (0)
; #define PG8_MMA(ai, bj, At, Bt) do { __builtin_amdgcn_s_setprio(1); _Pragma("unroll") for (int m = 0; m < 4; ++m) _Pragma("unroll") for (int n = 0; n < 2; ++n) _Pragma("unroll") for (int k = 0; k < 2; ++k) \
;         acc[ai][bj][m][n] = __builtin_amdgcn_mfma_f32_16x16x32_bf16(Bt[n][k], At[m][k], acc[ai][bj][m][n], 0, 0, 0); __builtin_amdgcn_s_setprio(0); } while (0)
; #define PG8_WAIT_V(n) asm volatile("s_waitcnt vmcnt(" #n ")" ::: "memory")
; #define PG8_WAIT_L(n) asm volatile("s_waitcnt lgkmcnt(" #n ")" ::: "memory")
; #define PG8_BAR __builtin_amdgcn_s_barrier()
; #define PG8_SCHED __builtin_amdgcn_sched_barrier(0)
; template <class Epi, class Sched, bool ALIGN_EPI = false, bool SP2 = false>
; __device__ __forceinline__ void gemm_phase(PG8_LAS unsigned char* lds, const Gemm g, const Sched& S, const Epi& E) {
;     ...
;         for (int t = 0; t < nt; t += 2) {
;     ...
;             PG8_LDB(B0, 1, 0); PG8_LDB(B1, 1, 1); PG8_SCHED; PG8_LDA(At, 1, 0); PG8_STAGE(PG8_SA(0, 1), a2 + hstep, voffA);
;             PG8_WAIT_V(8); PG8_WAIT_L(0); PG8_BAR; PG8_MMA(0, 0, At, B0); PG8_MMA(0, 1, At, B1); PG8_BAR; PG8_SCHED;
;             PG8_LDA(At, 1, 1); PG8_STAGE(PG8_SB(1, 0), b3, voffB); PG8_STAGE(PG8_SB(1, 1), b3 + hstep, voffB); PG8_STAGE(PG8_SA(1, 0), a3, voffA);
;             PG8_WAIT_V(8); PG8_WAIT_L(0); PG8_BAR; PG8_MMA(1, 0, At, B0); PG8_MMA(1, 1, At, B1); PG8_BAR; PG8_SCHED;
	s_add_i32 s55, 0, 0x18000
	s_add_i32 s56, 0, 0x1c000
	v_add_u32_e32 v162, s55, v145
	v_add_u32_e32 v178, s56, v145
	ds_read_b128 v[150:153], v162
	ds_read_b128 v[154:157], v162 offset:1024
	ds_read_b128 v[158:161], v162 offset:2048
	ds_read_b128 v[162:165], v162 offset:3072
	ds_read_b128 v[166:169], v178
	ds_read_b128 v[170:173], v178 offset:1024
	ds_read_b128 v[174:177], v178 offset:2048
	ds_read_b128 v[178:181], v178 offset:3072
	s_add_u32 s30, s30, 0x40000
	s_addc_u32 s31, s31, 0
	s_mov_b32 m0, s39
	v_lshl_add_u64 v[226:227], s[30:31], 0, v[134:135]
	ds_read_b128 v[182:185], v149 offset:32768
	ds_read_b128 v[192:195], v149 offset:33792
	ds_read_b128 v[196:199], v149 offset:34816
	ds_read_b128 v[200:203], v149 offset:35840
	ds_read_b128 v[204:207], v149 offset:36864
	ds_read_b128 v[208:211], v149 offset:37888
	ds_read_b128 v[212:215], v149 offset:38912
	ds_read_b128 v[216:219], v149 offset:39936
	global_load_lds_dwordx4 v[226:227], off
	v_lshl_add_u64 v[226:227], s[30:31], 0, v[130:131]
	s_mov_b32 m0, s40
	s_nop 0
	global_load_lds_dwordx4 v[226:227], off
	s_waitcnt vmcnt(8)
	s_waitcnt lgkmcnt(0)
	s_barrier
	s_setprio 1
	v_mfma_f32_16x16x32_bf16 v[124:127], v[150:153], v[182:185], v[124:127]
	v_mfma_f32_16x16x32_bf16 v[120:123], v[158:161], v[182:185], v[120:123]
	v_mfma_f32_16x16x32_bf16 v[108:111], v[150:153], v[196:199], v[108:111]
	v_mfma_f32_16x16x32_bf16 v[104:107], v[158:161], v[196:199], v[104:107]
	v_mfma_f32_16x16x32_bf16 v[92:95], v[150:153], v[204:207], v[92:95]
	v_mfma_f32_16x16x32_bf16 v[88:91], v[158:161], v[204:207], v[88:91]
	v_mfma_f32_16x16x32_bf16 v[76:79], v[150:153], v[212:215], v[76:79]
	v_mfma_f32_16x16x32_bf16 v[72:75], v[158:161], v[212:215], v[72:75]
	v_mfma_f32_16x16x32_bf16 v[124:127], v[154:157], v[192:195], v[124:127]
	v_mfma_f32_16x16x32_bf16 v[120:123], v[162:165], v[192:195], v[120:123]
	v_mfma_f32_16x16x32_bf16 v[108:111], v[154:157], v[200:203], v[108:111]
	v_mfma_f32_16x16x32_bf16 v[104:107], v[162:165], v[200:203], v[104:107]
	v_mfma_f32_16x16x32_bf16 v[92:95], v[154:157], v[208:211], v[92:95]
	v_mfma_f32_16x16x32_bf16 v[88:91], v[162:165], v[208:211], v[88:91]
	v_mfma_f32_16x16x32_bf16 v[76:79], v[154:157], v[216:219], v[76:79]
	v_mfma_f32_16x16x32_bf16 v[72:75], v[162:165], v[216:219], v[72:75]
	v_mfma_f32_16x16x32_bf16 v[116:119], v[166:169], v[182:185], v[116:119]
	v_mfma_f32_16x16x32_bf16 v[112:115], v[174:177], v[182:185], v[112:115]
	v_mfma_f32_16x16x32_bf16 v[100:103], v[166:169], v[196:199], v[100:103]
	v_mfma_f32_16x16x32_bf16 v[96:99], v[174:177], v[196:199], v[96:99]
	v_mfma_f32_16x16x32_bf16 v[84:87], v[166:169], v[204:207], v[84:87]
	v_mfma_f32_16x16x32_bf16 v[80:83], v[174:177], v[204:207], v[80:83]
	v_mfma_f32_16x16x32_bf16 v[68:71], v[166:169], v[212:215], v[68:71]
	v_mfma_f32_16x16x32_bf16 v[64:67], v[174:177], v[212:215], v[64:67]
	v_mfma_f32_16x16x32_bf16 v[116:119], v[170:173], v[192:195], v[116:119]
	v_mfma_f32_16x16x32_bf16 v[112:115], v[178:181], v[192:195], v[112:115]
	v_mfma_f32_16x16x32_bf16 v[100:103], v[170:173], v[200:203], v[100:103]
	v_mfma_f32_16x16x32_bf16 v[96:99], v[178:181], v[200:203], v[96:99]
	v_mfma_f32_16x16x32_bf16 v[84:87], v[170:173], v[208:211], v[84:87]
	v_mfma_f32_16x16x32_bf16 v[80:83], v[178:181], v[208:211], v[80:83]
	v_mfma_f32_16x16x32_bf16 v[68:71], v[170:173], v[216:219], v[68:71]
	v_mfma_f32_16x16x32_bf16 v[64:67], v[178:181], v[216:219], v[64:67]
	s_setprio 0
	s_barrier
	s_add_i32 s30, s55, s35
	v_lshl_add_u64 v[186:187], v[186:187], 0, s[4:5]
	s_mov_b32 m0, s30
	ds_read_b128 v[182:185], v149 offset:49152
	ds_read_b128 v[192:195], v149 offset:50176
	ds_read_b128 v[196:199], v149 offset:51200
	ds_read_b128 v[200:203], v149 offset:52224
	ds_read_b128 v[204:207], v149 offset:53248
	ds_read_b128 v[208:211], v149 offset:54272
	ds_read_b128 v[212:215], v149 offset:55296
	ds_read_b128 v[216:219], v149 offset:56320
	global_load_lds_dwordx4 v[186:187], off
	s_add_i32 m0, s30, 0x2000
	s_add_u32 s24, s24, 0x40080
	v_lshl_add_u64 v[186:187], v[220:221], 0, s[4:5]
	s_addc_u32 s25, s25, 0
	s_add_i32 s30, s56, s35
	global_load_lds_dwordx4 v[186:187], off
	v_lshl_add_u64 v[186:187], s[24:25], 0, v[132:133]
	s_mov_b32 m0, s30
	s_nop 0
	global_load_lds_dwordx4 v[186:187], off
	v_lshl_add_u64 v[186:187], s[24:25], 0, v[128:129]
	s_add_i32 m0, s30, 0x2000
	s_nop 0
	global_load_lds_dwordx4 v[186:187], off
	v_lshl_add_u64 v[186:187], v[222:223], 0, s[4:5]
	s_mov_b32 m0, s42
	s_nop 0
	global_load_lds_dwordx4 v[186:187], off
	v_lshl_add_u64 v[186:187], v[224:225], 0, s[4:5]
	s_mov_b32 m0, s43
	s_nop 0
	global_load_lds_dwordx4 v[186:187], off
	s_waitcnt vmcnt(8)
	s_waitcnt lgkmcnt(0)
	s_barrier
	s_setprio 1
	v_mfma_f32_16x16x32_bf16 v[60:63], v[150:153], v[182:185], v[60:63]
	v_mfma_f32_16x16x32_bf16 v[56:59], v[158:161], v[182:185], v[56:59]
	v_mfma_f32_16x16x32_bf16 v[44:47], v[150:153], v[196:199], v[44:47]
	v_mfma_f32_16x16x32_bf16 v[40:43], v[158:161], v[196:199], v[40:43]
	v_mfma_f32_16x16x32_bf16 v[28:31], v[150:153], v[204:207], v[28:31]
	v_mfma_f32_16x16x32_bf16 v[24:27], v[158:161], v[204:207], v[24:27]
	v_mfma_f32_16x16x32_bf16 v[12:15], v[150:153], v[212:215], v[12:15]
	v_mfma_f32_16x16x32_bf16 v[8:11], v[158:161], v[212:215], v[8:11]
	v_mfma_f32_16x16x32_bf16 v[60:63], v[154:157], v[192:195], v[60:63]
	v_mfma_f32_16x16x32_bf16 v[56:59], v[162:165], v[192:195], v[56:59]
	v_mfma_f32_16x16x32_bf16 v[44:47], v[154:157], v[200:203], v[44:47]
	v_mfma_f32_16x16x32_bf16 v[40:43], v[162:165], v[200:203], v[40:43]
	v_mfma_f32_16x16x32_bf16 v[28:31], v[154:157], v[208:211], v[28:31]
	v_mfma_f32_16x16x32_bf16 v[24:27], v[162:165], v[208:211], v[24:27]
	v_mfma_f32_16x16x32_bf16 v[12:15], v[154:157], v[216:219], v[12:15]
	v_mfma_f32_16x16x32_bf16 v[8:11], v[162:165], v[216:219], v[8:11]
	v_mfma_f32_16x16x32_bf16 v[52:55], v[166:169], v[182:185], v[52:55]
	v_mfma_f32_16x16x32_bf16 v[48:51], v[174:177], v[182:185], v[48:51]
	v_mfma_f32_16x16x32_bf16 v[36:39], v[166:169], v[196:199], v[36:39]
	v_mfma_f32_16x16x32_bf16 v[32:35], v[174:177], v[196:199], v[32:35]
	v_mfma_f32_16x16x32_bf16 v[20:23], v[166:169], v[204:207], v[20:23]
	v_mfma_f32_16x16x32_bf16 v[16:19], v[174:177], v[204:207], v[16:19]
	v_mfma_f32_16x16x32_bf16 v[4:7], v[166:169], v[212:215], v[4:7]
	v_mfma_f32_16x16x32_bf16 v[0:3], v[174:177], v[212:215], v[0:3]
	v_mfma_f32_16x16x32_bf16 v[52:55], v[170:173], v[192:195], v[52:55]
	v_mfma_f32_16x16x32_bf16 v[48:51], v[178:181], v[192:195], v[48:51]
	v_mfma_f32_16x16x32_bf16 v[36:39], v[170:173], v[200:203], v[36:39]
	v_mfma_f32_16x16x32_bf16 v[32:35], v[178:181], v[200:203], v[32:35]
	v_mfma_f32_16x16x32_bf16 v[20:23], v[170:173], v[208:211], v[20:23]
	v_mfma_f32_16x16x32_bf16 v[16:19], v[178:181], v[208:211], v[16:19]
	v_mfma_f32_16x16x32_bf16 v[4:7], v[170:173], v[216:219], v[4:7]
	v_mfma_f32_16x16x32_bf16 v[0:3], v[178:181], v[216:219], v[0:3]
	s_setprio 0
	s_barrier
	s_add_i32 s54, s54, 2
	s_add_u32 s22, s22, 0x100
	s_addc_u32 s23, s23, 0
	s_add_u32 s52, s52, 0x100
	s_addc_u32 s53, s53, 0

; __device__ __forceinline__ unsigned pk2(float lo, float hi) { return pg8::cvt_pk_bf16(lo, hi); }
; __device__ __forceinline__ float silu_f(float x) { return x * sigmoid_f(x); }
;     __device__ __forceinline__ void operator()(const f32x4 (&acc)[2][2][4][2], const pg8::Unit& u, int wr, int wc, int fr, int fq) const {
;         const int row0 = u.pm * 256 + wr * 64 + fr, col = u.pn * 128 + wc * 32 + 8 * fq;
; #pragma unroll
;         for (int ai = 0; ai < 2; ++ai)
; #pragma unroll
;             for (int m = 0; m < 4; ++m) {
;                 const int row = row0 + ai * 128 + m * 16;
;                 const float rs = sumsq ? rsqrtf(sumsq[row] * (1.f / 1024.f) + EPS) : 1.f;
;                 float o[8];
; #pragma unroll
;                 for (int n = 0; n < 2; ++n)
; #pragma unroll
;                     for (int e = 0; e < 4; ++e) { const float g = acc[ai][0][m][n][e] * rs, up = acc[ai][1][m][n][e] * rs; o[4 * n + e] = silu_f(g) * up; }
;                 u32x4 w; w.x = pk2(o[0], o[1]); w.y = pk2(o[2], o[3]); w.z = pk2(o[4], o[5]); w.w = pk2(o[6], o[7]);
;                 *(u32x4*)(H + (size_t)row * DFF + col) = w;
.LBB0_195:
	v_mul_f32_e32 v151, 0xbfb8aa3b, v124
	v_exp_f32_e32 v151, v151
	v_mul_f32_e32 v152, 0xbfb8aa3b, v125
	v_exp_f32_e32 v153, v152
	v_readlane_b32 s22, v235, 33
	v_add_f32_e32 v151, 1.0, v151
	v_rcp_f32_e32 v151, v151
	v_add_f32_e32 v153, 1.0, v153
	v_rcp_f32_e32 v154, v153
	v_lshl_or_b32 v152, s49, 7, v146
	v_mul_f32_e32 v124, v124, v151
	v_mul_f32_e32 v116, v124, v116
	v_mul_f32_e32 v124, v125, v154
	v_mul_f32_e32 v125, 0xbfb8aa3b, v126
	v_exp_f32_e32 v125, v125
	v_mul_f32_e32 v151, 0xbfb8aa3b, v127
	v_exp_f32_e32 v151, v151
	v_mul_f32_e32 v117, v124, v117
	v_add_f32_e32 v124, 1.0, v125
	v_rcp_f32_e32 v124, v124
	v_add_f32_e32 v125, 1.0, v151
	v_mul_f32_e32 v151, 0xbfb8aa3b, v120
	v_rcp_f32_e32 v125, v125
	v_exp_f32_e32 v151, v151
	v_mul_f32_e32 v124, v126, v124
	v_mul_f32_e32 v118, v124, v118
	v_mul_f32_e32 v124, v127, v125
	v_add_f32_e32 v125, 1.0, v151
	v_rcp_f32_e32 v125, v125
	v_mul_f32_e32 v126, 0xbfb8aa3b, v121
	v_exp_f32_e32 v126, v126
	v_mul_f32_e32 v119, v124, v119
	v_mul_f32_e32 v120, v120, v125
	v_mul_f32_e32 v112, v120, v112
	v_add_f32_e32 v120, 1.0, v126
	v_mul_f32_e32 v124, 0xbfb8aa3b, v122
	v_rcp_f32_e32 v120, v120
	v_exp_f32_e32 v124, v124
	v_mul_f32_e32 v125, 0xbfb8aa3b, v123
	v_exp_f32_e32 v125, v125
	v_mul_f32_e32 v120, v121, v120
	v_add_f32_e32 v121, 1.0, v124
	v_rcp_f32_e32 v121, v121
	v_add_f32_e32 v124, 1.0, v125
	v_rcp_f32_e32 v124, v124
	v_mul_f32_e32 v113, v120, v113
	v_mul_f32_e32 v120, v122, v121
	v_mul_f32_e32 v122, 0xbfb8aa3b, v108
	v_mul_f32_e32 v114, v120, v114
	v_mul_f32_e32 v120, v123, v124
	v_readlane_b32 s23, v235, 34
	v_exp_f32_e32 v122, v122
	v_mul_f32_e32 v123, 0xbfb8aa3b, v109
	v_lshl_add_u32 v228, s20, 8, v144
	v_ashrrev_i32_e32 v153, 31, v152
	v_mul_f32_e32 v115, v120, v115
	v_cvt_pk_bf16_f32 v116, v116, v117
	v_cvt_pk_bf16_f32 v117, v118, v119
	v_cvt_pk_bf16_f32 v118, v112, v113
	v_mov_b64_e32 v[112:113], s[22:23]
	v_exp_f32_e32 v123, v123
	v_cvt_pk_bf16_f32 v119, v114, v115
	v_mad_i64_i32 v[120:121], s[22:23], v228, s48, v[112:113]
	v_lshlrev_b64 v[114:115], 1, v[152:153]
	v_lshl_add_u64 v[120:121], v[120:121], 0, v[114:115]
	global_store_dwordx4 v[120:121], v[116:119], off
	s_andn2_b64 vcc, exec, s[0:1]
	s_mov_b64 s[0:1], -1
	v_add_f32_e32 v116, 1.0, v122
	v_rcp_f32_e32 v116, v116
	v_add_f32_e32 v117, 1.0, v123
	v_rcp_f32_e32 v117, v117
	v_or_b32_e32 v118, 16, v228
	v_mul_f32_e32 v108, v108, v116
	v_mul_f32_e32 v100, v108, v100
	v_mul_f32_e32 v108, v109, v117
	v_mul_f32_e32 v109, 0xbfb8aa3b, v110
	v_exp_f32_e32 v109, v109
	v_mul_f32_e32 v116, 0xbfb8aa3b, v111
	v_exp_f32_e32 v116, v116
	v_mul_f32_e32 v101, v108, v101
	v_add_f32_e32 v108, 1.0, v109
	v_rcp_f32_e32 v108, v108
	v_add_f32_e32 v109, 1.0, v116
	v_mul_f32_e32 v116, 0xbfb8aa3b, v104
	v_rcp_f32_e32 v109, v109
	v_exp_f32_e32 v116, v116
	v_mul_f32_e32 v108, v110, v108
	v_mul_f32_e32 v102, v108, v102
	v_mul_f32_e32 v108, v111, v109
	v_add_f32_e32 v109, 1.0, v116
	v_rcp_f32_e32 v109, v109
	v_mul_f32_e32 v110, 0xbfb8aa3b, v105
	v_exp_f32_e32 v110, v110
	v_mul_f32_e32 v103, v108, v103
	v_mul_f32_e32 v104, v104, v109
	v_mul_f32_e32 v104, v104, v96
	v_add_f32_e32 v96, 1.0, v110
	v_mul_f32_e32 v108, 0xbfb8aa3b, v106
	v_rcp_f32_e32 v96, v96
	v_exp_f32_e32 v108, v108
	v_mul_f32_e32 v109, 0xbfb8aa3b, v107
	v_exp_f32_e32 v109, v109
	v_mul_f32_e32 v96, v105, v96
	v_add_f32_e32 v105, 1.0, v108
	v_rcp_f32_e32 v105, v105
	v_add_f32_e32 v108, 1.0, v109
	v_rcp_f32_e32 v108, v108
	v_mul_f32_e32 v109, v96, v97
	v_mul_f32_e32 v96, v106, v105
	v_mul_f32_e32 v105, v96, v98
	v_mul_f32_e32 v96, v107, v108
	v_mul_f32_e32 v99, v96, v99
	v_cvt_pk_bf16_f32 v96, v100, v101
	v_cvt_pk_bf16_f32 v97, v102, v103
	v_mul_f32_e32 v102, 0xbfb8aa3b, v92
	v_exp_f32_e32 v102, v102
	v_mul_f32_e32 v103, 0xbfb8aa3b, v93
	v_exp_f32_e32 v103, v103
	v_mad_i64_i32 v[100:101], s[22:23], v118, s48, v[112:113]
	v_lshl_add_u64 v[100:101], v[100:101], 0, v[114:115]
	v_cvt_pk_bf16_f32 v98, v104, v109
	v_cvt_pk_bf16_f32 v99, v105, v99
	global_store_dwordx4 v[100:101], v[96:99], off
	s_nop 1
	v_add_f32_e32 v96, 1.0, v102
	v_rcp_f32_e32 v96, v96
	v_add_f32_e32 v97, 1.0, v103
	v_rcp_f32_e32 v97, v97
	v_or_b32_e32 v98, 32, v228
	v_mul_f32_e32 v92, v92, v96
	v_mul_f32_e32 v84, v92, v84
	v_mul_f32_e32 v92, v93, v97
	v_mul_f32_e32 v93, 0xbfb8aa3b, v94
	v_exp_f32_e32 v93, v93
	v_mul_f32_e32 v96, 0xbfb8aa3b, v95
	v_exp_f32_e32 v96, v96
	v_mul_f32_e32 v85, v92, v85
	v_add_f32_e32 v92, 1.0, v93
	v_rcp_f32_e32 v92, v92
	v_add_f32_e32 v93, 1.0, v96
	v_mul_f32_e32 v96, 0xbfb8aa3b, v88
	v_rcp_f32_e32 v93, v93
	v_exp_f32_e32 v96, v96
	v_mul_f32_e32 v92, v94, v92
	v_mul_f32_e32 v86, v92, v86
	v_mul_f32_e32 v92, v95, v93
	v_add_f32_e32 v93, 1.0, v96
	v_rcp_f32_e32 v93, v93
	v_mul_f32_e32 v94, 0xbfb8aa3b, v89
	v_exp_f32_e32 v94, v94
	v_mul_f32_e32 v87, v92, v87
	v_mul_f32_e32 v88, v88, v93
	v_mul_f32_e32 v88, v88, v80
	v_add_f32_e32 v80, 1.0, v94
	v_mul_f32_e32 v92, 0xbfb8aa3b, v90
	v_rcp_f32_e32 v80, v80
	v_exp_f32_e32 v92, v92
	v_mul_f32_e32 v93, 0xbfb8aa3b, v91
	v_exp_f32_e32 v93, v93
	v_mul_f32_e32 v80, v89, v80
	v_add_f32_e32 v89, 1.0, v92
	v_rcp_f32_e32 v89, v89
	v_add_f32_e32 v92, 1.0, v93
	v_rcp_f32_e32 v92, v92
	v_mul_f32_e32 v93, v80, v81
	v_mul_f32_e32 v80, v90, v89
	v_mul_f32_e32 v89, v80, v82
	v_mul_f32_e32 v80, v91, v92
	v_mul_f32_e32 v83, v80, v83
	v_cvt_pk_bf16_f32 v80, v84, v85
	v_cvt_pk_bf16_f32 v81, v86, v87
	v_mul_f32_e32 v86, 0xbfb8aa3b, v76
	v_exp_f32_e32 v86, v86
	v_mul_f32_e32 v87, 0xbfb8aa3b, v77
	v_exp_f32_e32 v87, v87
	v_mad_i64_i32 v[84:85], s[22:23], v98, s48, v[112:113]
	v_lshl_add_u64 v[84:85], v[84:85], 0, v[114:115]
	v_cvt_pk_bf16_f32 v82, v88, v93
	v_cvt_pk_bf16_f32 v83, v89, v83
; #define PG8_BAR __builtin_amdgcn_s_barrier()
; __device__ __forceinline__ unsigned pk2(float lo, float hi) { return pg8::cvt_pk_bf16(lo, hi); }
; __device__ __forceinline__ float silu_f(float x) { return x * sigmoid_f(x); }
; template <class Epi, class Sched, bool ALIGN_EPI = false, bool SP2 = false>
; __device__ __forceinline__ void gemm_phase(PG8_LAS unsigned char* lds, const Gemm g, const Sched& S, const Epi& E) {
;     ...
;         if (!has_next) break;
; #pragma unroll
;         for (int a = 0; a < 2; ++a)
; #pragma unroll
;             for (int b = 0; b < 2; ++b)
; #pragma unroll
;                 for (int m = 0; m < 4; ++m)
; #pragma unroll
;                     for (int n = 0; n < 2; ++n) acc[a][b][m][n] = (f32x4){0.f, 0.f, 0.f, 0.f};
;         cur = nxt; cA = nA; cB = nB; ++ui;
;         if constexpr (ALIGN_EPI) { if (wr == 1) PG8_BAR; }
;     __device__ __forceinline__ void operator()(const f32x4 (&acc)[2][2][4][2], const pg8::Unit& u, int wr, int wc, int fr, int fq) const {
;     ...
;                 const int row = row0 + ai * 128 + m * 16;
;                 const float rs = sumsq ? rsqrtf(sumsq[row] * (1.f / 1024.f) + EPS) : 1.f;
;                 float o[8];
; #pragma unroll
;                 for (int n = 0; n < 2; ++n)
; #pragma unroll
;                     for (int e = 0; e < 4; ++e) { const float g = acc[ai][0][m][n][e] * rs, up = acc[ai][1][m][n][e] * rs; o[4 * n + e] = silu_f(g) * up; }
;                 u32x4 w; w.x = pk2(o[0], o[1]); w.y = pk2(o[2], o[3]); w.z = pk2(o[4], o[5]); w.w = pk2(o[6], o[7]);
;                 *(u32x4*)(H + (size_t)row * DFF + col) = w;
	global_store_dwordx4 v[84:85], v[80:83], off
	s_nop 1
	v_add_f32_e32 v80, 1.0, v86
	v_rcp_f32_e32 v80, v80
	v_add_f32_e32 v81, 1.0, v87
	v_rcp_f32_e32 v81, v81
	v_or_b32_e32 v82, 48, v228
	v_mul_f32_e32 v76, v76, v80
	v_mul_f32_e32 v68, v76, v68
	v_mul_f32_e32 v76, v77, v81
	v_mul_f32_e32 v77, 0xbfb8aa3b, v78
	v_exp_f32_e32 v77, v77
	v_mul_f32_e32 v80, 0xbfb8aa3b, v79
	v_exp_f32_e32 v80, v80
	v_mul_f32_e32 v69, v76, v69
	v_add_f32_e32 v76, 1.0, v77
	v_rcp_f32_e32 v76, v76
	v_add_f32_e32 v77, 1.0, v80
	v_mul_f32_e32 v80, 0xbfb8aa3b, v72
	v_rcp_f32_e32 v77, v77
	v_exp_f32_e32 v80, v80
	v_mul_f32_e32 v76, v78, v76
	v_mul_f32_e32 v70, v76, v70
	v_mul_f32_e32 v76, v79, v77
	v_add_f32_e32 v77, 1.0, v80
	v_rcp_f32_e32 v77, v77
	v_mul_f32_e32 v78, 0xbfb8aa3b, v73
	v_exp_f32_e32 v78, v78
	v_mul_f32_e32 v71, v76, v71
	v_mul_f32_e32 v72, v72, v77
	v_mul_f32_e32 v72, v72, v64
	v_add_f32_e32 v64, 1.0, v78
	v_mul_f32_e32 v76, 0xbfb8aa3b, v74
	v_rcp_f32_e32 v64, v64
	v_exp_f32_e32 v76, v76
	v_mul_f32_e32 v77, 0xbfb8aa3b, v75
	v_exp_f32_e32 v77, v77
	v_mul_f32_e32 v64, v73, v64
	v_add_f32_e32 v73, 1.0, v76
	v_rcp_f32_e32 v73, v73
	v_add_f32_e32 v76, 1.0, v77
	v_rcp_f32_e32 v76, v76
	v_mul_f32_e32 v77, v64, v65
	v_mul_f32_e32 v64, v74, v73
	v_mul_f32_e32 v73, v64, v66
	v_mul_f32_e32 v64, v75, v76
	v_mul_f32_e32 v67, v64, v67
	v_cvt_pk_bf16_f32 v64, v68, v69
	v_cvt_pk_bf16_f32 v65, v70, v71
	v_mul_f32_e32 v70, 0xbfb8aa3b, v60
	v_exp_f32_e32 v70, v70
	v_mul_f32_e32 v71, 0xbfb8aa3b, v61
	v_exp_f32_e32 v71, v71
	v_mad_i64_i32 v[68:69], s[22:23], v82, s48, v[112:113]
	v_lshl_add_u64 v[68:69], v[68:69], 0, v[114:115]
	v_cvt_pk_bf16_f32 v66, v72, v77
	v_cvt_pk_bf16_f32 v67, v73, v67
	global_store_dwordx4 v[68:69], v[64:67], off
	s_mov_b32 s98, 1
	s_cbranch_vccnz .LBB0_188
	s_andn2_b64 vcc, exec, s[2:3]
	s_cbranch_vccnz .LBB0_187
	s_barrier
	s_branch .LBB0_187
; __device__ __forceinline__ unsigned pk2(float lo, float hi) { return pg8::cvt_pk_bf16(lo, hi); }
; __device__ __forceinline__ float silu_f(float x) { return x * sigmoid_f(x); }
;     __device__ __forceinline__ void operator()(const f32x4 (&acc)[2][2][4][2], const pg8::Unit& u, int wr, int wc, int fr, int fq) const {
;     ...
;         for (int ai = 0; ai < 2; ++ai)
; #pragma unroll
;             for (int m = 0; m < 4; ++m) {
;                 const int row = row0 + ai * 128 + m * 16;
;                 const float rs = sumsq ? rsqrtf(sumsq[row] * (1.f / 1024.f) + EPS) : 1.f;
;                 float o[8];
; #pragma unroll
;                 for (int n = 0; n < 2; ++n)
; #pragma unroll
;                     for (int e = 0; e < 4; ++e) { const float g = acc[ai][0][m][n][e] * rs, up = acc[ai][1][m][n][e] * rs; o[4 * n + e] = silu_f(g) * up; }
;                 u32x4 w; w.x = pk2(o[0], o[1]); w.y = pk2(o[2], o[3]); w.z = pk2(o[4], o[5]); w.w = pk2(o[6], o[7]);
;                 *(u32x4*)(H + (size_t)row * DFF + col) = w;
.Lp1_tail:
	s_nop 1
	v_add_f32_e32 v64, 1.0, v70
	v_rcp_f32_e32 v64, v64
	v_add_f32_e32 v65, 1.0, v71
	v_rcp_f32_e32 v65, v65
	v_add_u32_e32 v66, 0x80, v228
	v_mul_f32_e32 v60, v60, v64
	v_mul_f32_e32 v52, v60, v52
	v_mul_f32_e32 v60, v61, v65
	v_mul_f32_e32 v61, 0xbfb8aa3b, v62
	v_exp_f32_e32 v61, v61
	v_mul_f32_e32 v64, 0xbfb8aa3b, v63
	v_exp_f32_e32 v64, v64
	v_mul_f32_e32 v53, v60, v53
	v_add_f32_e32 v60, 1.0, v61
	v_rcp_f32_e32 v60, v60
	v_add_f32_e32 v61, 1.0, v64
	v_mul_f32_e32 v64, 0xbfb8aa3b, v56
	v_rcp_f32_e32 v61, v61
	v_exp_f32_e32 v64, v64
	v_mul_f32_e32 v60, v62, v60
	v_mul_f32_e32 v54, v60, v54
	v_mul_f32_e32 v60, v63, v61
	v_add_f32_e32 v61, 1.0, v64
	v_rcp_f32_e32 v61, v61
	v_mul_f32_e32 v62, 0xbfb8aa3b, v57
	v_exp_f32_e32 v62, v62
	v_mul_f32_e32 v55, v60, v55
	v_mul_f32_e32 v56, v56, v61
	v_mul_f32_e32 v56, v56, v48
	v_add_f32_e32 v48, 1.0, v62
	v_mul_f32_e32 v60, 0xbfb8aa3b, v58
	v_rcp_f32_e32 v48, v48
	v_exp_f32_e32 v60, v60
	v_mul_f32_e32 v61, 0xbfb8aa3b, v59
	v_exp_f32_e32 v61, v61
	v_mul_f32_e32 v48, v57, v48
	v_add_f32_e32 v57, 1.0, v60
	v_rcp_f32_e32 v57, v57
	v_add_f32_e32 v60, 1.0, v61
	v_rcp_f32_e32 v60, v60
	v_mul_f32_e32 v61, v48, v49
	v_mul_f32_e32 v48, v58, v57
	v_mul_f32_e32 v57, v48, v50
	v_mul_f32_e32 v48, v59, v60
	v_mul_f32_e32 v51, v48, v51
	v_cvt_pk_bf16_f32 v48, v52, v53
	v_cvt_pk_bf16_f32 v49, v54, v55
	v_mul_f32_e32 v54, 0xbfb8aa3b, v44
	v_exp_f32_e32 v54, v54
	v_mul_f32_e32 v55, 0xbfb8aa3b, v45
	v_exp_f32_e32 v55, v55
	v_mad_i64_i32 v[52:53], s[100:101], v66, s48, v[112:113]
	v_lshl_add_u64 v[52:53], v[52:53], 0, v[114:115]
	v_cvt_pk_bf16_f32 v50, v56, v61
	v_cvt_pk_bf16_f32 v51, v57, v51
	global_store_dwordx4 v[52:53], v[48:51], off
	s_nop 1
	v_add_f32_e32 v48, 1.0, v54
	v_rcp_f32_e32 v48, v48
	v_add_f32_e32 v49, 1.0, v55
	v_rcp_f32_e32 v49, v49
	v_add_u32_e32 v50, 0x90, v228
	v_mul_f32_e32 v44, v44, v48
	v_mul_f32_e32 v36, v44, v36
	v_mul_f32_e32 v44, v45, v49
	v_mul_f32_e32 v45, 0xbfb8aa3b, v46
	v_exp_f32_e32 v45, v45
	v_mul_f32_e32 v48, 0xbfb8aa3b, v47
	v_exp_f32_e32 v48, v48
	v_mul_f32_e32 v37, v44, v37
	v_add_f32_e32 v44, 1.0, v45
	v_rcp_f32_e32 v44, v44
	v_add_f32_e32 v45, 1.0, v48
	v_mul_f32_e32 v48, 0xbfb8aa3b, v40
	v_rcp_f32_e32 v45, v45
	v_exp_f32_e32 v48, v48
	v_mul_f32_e32 v44, v46, v44
	v_mul_f32_e32 v38, v44, v38
	v_mul_f32_e32 v44, v47, v45
	v_add_f32_e32 v45, 1.0, v48
	v_rcp_f32_e32 v45, v45
	v_mul_f32_e32 v46, 0xbfb8aa3b, v41
	v_exp_f32_e32 v46, v46
	v_mul_f32_e32 v39, v44, v39
	v_mul_f32_e32 v40, v40, v45
	v_mul_f32_e32 v40, v40, v32
	v_add_f32_e32 v32, 1.0, v46
	v_mul_f32_e32 v44, 0xbfb8aa3b, v42
	v_rcp_f32_e32 v32, v32
	v_exp_f32_e32 v44, v44
	v_mul_f32_e32 v45, 0xbfb8aa3b, v43
	v_exp_f32_e32 v45, v45
	v_mul_f32_e32 v32, v41, v32
	v_add_f32_e32 v41, 1.0, v44
	v_rcp_f32_e32 v41, v41
	v_add_f32_e32 v44, 1.0, v45
	v_rcp_f32_e32 v44, v44
	v_mul_f32_e32 v45, v32, v33
	v_mul_f32_e32 v32, v42, v41
	v_mul_f32_e32 v41, v32, v34
	v_mul_f32_e32 v32, v43, v44
	v_mul_f32_e32 v35, v32, v35
	v_cvt_pk_bf16_f32 v32, v36, v37
	v_cvt_pk_bf16_f32 v33, v38, v39
	v_mul_f32_e32 v38, 0xbfb8aa3b, v28
	v_exp_f32_e32 v38, v38
	v_mul_f32_e32 v39, 0xbfb8aa3b, v29
	v_exp_f32_e32 v39, v39
	v_mad_i64_i32 v[36:37], s[100:101], v50, s48, v[112:113]
	v_lshl_add_u64 v[36:37], v[36:37], 0, v[114:115]
	v_cvt_pk_bf16_f32 v34, v40, v45
	v_cvt_pk_bf16_f32 v35, v41, v35
	global_store_dwordx4 v[36:37], v[32:35], off
	s_nop 1
	v_add_f32_e32 v32, 1.0, v38
	v_rcp_f32_e32 v32, v32
	v_add_f32_e32 v33, 1.0, v39
	v_rcp_f32_e32 v33, v33
	v_add_u32_e32 v34, 0xa0, v228
	v_mul_f32_e32 v28, v28, v32
	v_mul_f32_e32 v20, v28, v20
	v_mul_f32_e32 v28, v29, v33
	v_mul_f32_e32 v29, 0xbfb8aa3b, v30
	v_exp_f32_e32 v29, v29
	v_mul_f32_e32 v32, 0xbfb8aa3b, v31
	v_exp_f32_e32 v32, v32
	v_mul_f32_e32 v21, v28, v21
	v_add_f32_e32 v28, 1.0, v29
	v_rcp_f32_e32 v28, v28
	v_add_f32_e32 v29, 1.0, v32
	v_mul_f32_e32 v32, 0xbfb8aa3b, v24
	v_rcp_f32_e32 v29, v29
	v_exp_f32_e32 v32, v32
	v_mul_f32_e32 v28, v30, v28
	v_mul_f32_e32 v22, v28, v22
	v_mul_f32_e32 v28, v31, v29
	v_add_f32_e32 v29, 1.0, v32
	v_rcp_f32_e32 v29, v29
	v_mul_f32_e32 v30, 0xbfb8aa3b, v25
	v_exp_f32_e32 v30, v30
	v_mul_f32_e32 v23, v28, v23
	v_mul_f32_e32 v24, v24, v29
	v_mul_f32_e32 v24, v24, v16
	v_add_f32_e32 v16, 1.0, v30
	v_mul_f32_e32 v28, 0xbfb8aa3b, v26
	v_rcp_f32_e32 v16, v16
	v_exp_f32_e32 v28, v28
	v_mul_f32_e32 v29, 0xbfb8aa3b, v27
	v_exp_f32_e32 v29, v29
	v_mul_f32_e32 v16, v25, v16
	v_add_f32_e32 v25, 1.0, v28
	v_rcp_f32_e32 v25, v25
	v_add_f32_e32 v28, 1.0, v29
	v_rcp_f32_e32 v28, v28
	v_mul_f32_e32 v29, v16, v17
	v_mul_f32_e32 v16, v26, v25
	v_mul_f32_e32 v25, v16, v18
	v_mul_f32_e32 v16, v27, v28
	v_mul_f32_e32 v19, v16, v19
	v_cvt_pk_bf16_f32 v16, v20, v21
	v_cvt_pk_bf16_f32 v17, v22, v23
	v_mul_f32_e32 v22, 0xbfb8aa3b, v12
	v_exp_f32_e32 v22, v22
	v_mul_f32_e32 v23, 0xbfb8aa3b, v13
	v_exp_f32_e32 v23, v23
	v_mad_i64_i32 v[20:21], s[100:101], v34, s48, v[112:113]
	v_lshl_add_u64 v[20:21], v[20:21], 0, v[114:115]
	v_cvt_pk_bf16_f32 v18, v24, v29
	v_cvt_pk_bf16_f32 v19, v25, v19
	global_store_dwordx4 v[20:21], v[16:19], off
	s_nop 1
	v_add_f32_e32 v16, 1.0, v22
	v_rcp_f32_e32 v16, v16
	v_add_f32_e32 v17, 1.0, v23
	v_rcp_f32_e32 v17, v17
	v_add_u32_e32 v18, 0xb0, v228
	v_mul_f32_e32 v12, v12, v16
	v_mul_f32_e32 v4, v12, v4
	v_mul_f32_e32 v12, v13, v17
	v_mul_f32_e32 v13, 0xbfb8aa3b, v14
	v_exp_f32_e32 v13, v13
	v_mul_f32_e32 v16, 0xbfb8aa3b, v15
	v_exp_f32_e32 v16, v16
	v_mul_f32_e32 v5, v12, v5
	v_add_f32_e32 v12, 1.0, v13
	v_rcp_f32_e32 v12, v12
	v_add_f32_e32 v13, 1.0, v16
	v_mul_f32_e32 v16, 0xbfb8aa3b, v8
	v_rcp_f32_e32 v13, v13
	v_exp_f32_e32 v16, v16
	v_mul_f32_e32 v12, v14, v12
	v_mul_f32_e32 v6, v12, v6
	v_mul_f32_e32 v12, v15, v13
	v_add_f32_e32 v13, 1.0, v16
	v_rcp_f32_e32 v13, v13
	v_mul_f32_e32 v14, 0xbfb8aa3b, v9
	v_exp_f32_e32 v14, v14
	v_mul_f32_e32 v7, v12, v7
	v_mul_f32_e32 v8, v8, v13
	v_mul_f32_e32 v8, v8, v0
	v_add_f32_e32 v0, 1.0, v14
	v_mul_f32_e32 v12, 0xbfb8aa3b, v10
	v_rcp_f32_e32 v0, v0
	v_exp_f32_e32 v12, v12
	v_mul_f32_e32 v13, 0xbfb8aa3b, v11
	v_exp_f32_e32 v13, v13
	v_mul_f32_e32 v0, v9, v0
	v_add_f32_e32 v9, 1.0, v12
	v_rcp_f32_e32 v9, v9
	v_add_f32_e32 v12, 1.0, v13
	v_rcp_f32_e32 v12, v12
	v_mul_f32_e32 v13, v0, v1
	v_mul_f32_e32 v0, v10, v9
	v_mul_f32_e32 v9, v0, v2
	v_mul_f32_e32 v0, v11, v12
	v_mul_f32_e32 v3, v0, v3
	v_cvt_pk_bf16_f32 v0, v4, v5
	v_mad_i64_i32 v[4:5], s[100:101], v18, s48, v[112:113]
	v_lshl_add_u64 v[4:5], v[4:5], 0, v[114:115]
	v_cvt_pk_bf16_f32 v1, v6, v7
	v_cvt_pk_bf16_f32 v2, v8, v13
	v_cvt_pk_bf16_f32 v3, v9, v3
	global_store_dwordx4 v[4:5], v[0:3], off
